# K-loop MFMA order changed to accumulator-inner (k=0,k=1 back to back per accumulator, same accumulation order) on top of v18 stack
# speedup vs baseline: 1.0131x; 1.0131x over previous
; #define PG8_STAGE(bufoff, gbase, voff) do { _Pragma("unroll") for (int _i = 0; _i < 2; ++_i) \
;         __builtin_amdgcn_global_load_lds((const unsigned*)((const char*)(gbase) + (voff)[_i]), (PG8_LAS unsigned*)(lds + (bufoff) + ldsw + _i * 8192), 16, 0, 0); } while (0)
; #define PG8_LDA(dst, b, h) do { _Pragma("unroll") for (int m = 0; m < 4; ++m) _Pragma("unroll") for (int k = 0; k < 2; ++k) dst[m][k] = *(const PG8_LAS bf16x8*)(lds + PG8_SA(b, h) + aoff + m * 2048 + k * 1024); } while (0)
; #define PG8_LDB(dst, b, h) do { _Pragma("unroll") for (int n = 0; n < 2; ++n) _Pragma("unroll") for (int k = 0; k < 2; ++k) dst[n][k] = *(const PG8_LAS bf16x8*)(lds + PG8_SB(b, h) + boff + n * 2048 + k * 1024); } while (0)
; #define PG8_MMA(ai, bj, At, Bt) do { __builtin_amdgcn_s_setprio(1); _Pragma("unroll") for (int m = 0; m < 4; ++m) _Pragma("unroll") for (int n = 0; n < 2; ++n) _Pragma("unroll") for (int k = 0; k < 2; ++k) \
;         acc[ai][bj][m][n] = __builtin_amdgcn_mfma_f32_16x16x32_bf16(Bt[n][k], At[m][k], acc[ai][bj][m][n], 0, 0, 0); __builtin_amdgcn_s_setprio(0); } while (0)
; #define PG8_WAIT_V(n) asm volatile("s_waitcnt vmcnt(" #n ")" ::: "memory")
; #define PG8_WAIT_L(n) asm volatile("s_waitcnt lgkmcnt(" #n ")" ::: "memory")
; template <class Epi, class Sched, bool ALIGN_EPI = false, bool SP2 = false>
; __device__ __forceinline__ void gemm_phase(PG8_LAS unsigned char* lds, const Gemm g, const Sched& S, const Epi& E, const int wave_s) {
;     ...
;             const bool last = (t == nt - 2);
;             const char* a1 = cA + (size_t)(t + 1) * kstep;
;             const char* a2 = last ? nA : cA + (size_t)(t + 2) * kstep; const char* b2 = last ? nB : cB + (size_t)(t + 2) * kstep;
;             const char* a3 = a2 + kstep; const char* b3 = b2 + kstep;
;             if (last && has_next) S.a_ready(nxt);
;             if constexpr (SP2) {
;             PG8_LDB(B0, 0, 0); PG8_LDB(B1, 0, 1); PG8_SCHED; PG8_LDA(At, 0, 0); PG8_STAGE(PG8_SA(1, 1), a1 + hstep, voffA);
;             PG8_WAIT_V(8); PG8_WAIT_L(0); PG8_BAR; PG8_MMA(0, 0, At, B0); PG8_MMA(0, 1, At, B1); PG8_BAR; PG8_SCHED;
;             PG8_LDA(At, 0, 1); PG8_STAGE(PG8_SB(0, 0), b2, voffB); PG8_STAGE(PG8_SB(0, 1), b2 + bhstep, voffB); PG8_STAGE(PG8_SA(0, 0), a2, voffA);
;             PG8_WAIT_V(8); PG8_WAIT_L(0); PG8_BAR; PG8_MMA(1, 0, At, B0); PG8_MMA(1, 1, At, B1); PG8_BAR; PG8_SCHED;
.LBB0_136:
	s_add_u32 s42, s20, 0xfffc0080
	s_addc_u32 s43, s21, -1
	s_add_i32 s71, 0, 0x10000
	s_cmp_eq_u32 s70, 12
	s_cselect_b32 s45, s65, s43
	s_cselect_b32 s44, s66, s42
	v_add_u32_e32 v0, s71, v171
	s_cselect_b32 s43, s53, s69
	s_cselect_b32 s42, s67, s68
	s_add_i32 s74, 0, 0x14000
	ds_read_b128 v[146:149], v0
	ds_read_b128 v[150:153], v0 offset:1024
	ds_read_b128 v[154:157], v0 offset:2048
	ds_read_b128 v[158:161], v0 offset:3072
	v_add_u32_e32 v0, s74, v171
	ds_read_b128 v[162:165], v0
	ds_read_b128 v[166:169], v0 offset:1024
	s_nop 0
	ds_read_b128 v[182:185], v0 offset:2048
	ds_read_b128 v[186:189], v0 offset:3072
	v_lshl_add_u64 v[224:225], s[20:21], 0, v[142:143]
	s_add_i32 m0, s7, 0xc000
	ds_read_b128 v[190:193], v177
	ds_read_b128 v[194:197], v177 offset:1024
	ds_read_b128 v[198:201], v177 offset:2048
	ds_read_b128 v[204:207], v177 offset:3072
	ds_read_b128 v[208:211], v177 offset:4096
	ds_read_b128 v[212:215], v177 offset:5120
	ds_read_b128 v[216:219], v177 offset:6144
	ds_read_b128 v[220:223], v177 offset:7168
	global_load_lds_dwordx4 v[224:225], off
	v_lshl_add_u64 v[224:225], s[20:21], 0, v[144:145]
	s_add_i32 m0, s7, 0xe000
	s_nop 0
	global_load_lds_dwordx4 v[224:225], off
	s_waitcnt vmcnt(8)
	s_waitcnt lgkmcnt(0)
	s_barrier
	s_setprio 1
	s_waitcnt lgkmcnt(0)
	v_mfma_f32_16x16x32_bf16 v[126:129], v[146:149], v[190:193], v[126:129]
	v_mfma_f32_16x16x32_bf16 v[126:129], v[150:153], v[194:197], v[126:129]
	v_mfma_f32_16x16x32_bf16 v[122:125], v[154:157], v[190:193], v[122:125]
	v_mfma_f32_16x16x32_bf16 v[122:125], v[158:161], v[194:197], v[122:125]
	v_mfma_f32_16x16x32_bf16 v[110:113], v[146:149], v[198:201], v[110:113]
	v_mfma_f32_16x16x32_bf16 v[110:113], v[150:153], v[204:207], v[110:113]
	v_mfma_f32_16x16x32_bf16 v[106:109], v[154:157], v[198:201], v[106:109]
	v_mfma_f32_16x16x32_bf16 v[106:109], v[158:161], v[204:207], v[106:109]
	v_mfma_f32_16x16x32_bf16 v[94:97], v[146:149], v[208:211], v[94:97]
	v_mfma_f32_16x16x32_bf16 v[94:97], v[150:153], v[212:215], v[94:97]
	v_mfma_f32_16x16x32_bf16 v[90:93], v[154:157], v[208:211], v[90:93]
	v_mfma_f32_16x16x32_bf16 v[90:93], v[158:161], v[212:215], v[90:93]
	v_mfma_f32_16x16x32_bf16 v[78:81], v[146:149], v[216:219], v[78:81]
	v_mfma_f32_16x16x32_bf16 v[78:81], v[150:153], v[220:223], v[78:81]
	v_mfma_f32_16x16x32_bf16 v[74:77], v[154:157], v[216:219], v[74:77]
	v_mfma_f32_16x16x32_bf16 v[74:77], v[158:161], v[220:223], v[74:77]
	s_setprio 0
	s_setprio 1
	v_mfma_f32_16x16x32_bf16 v[118:121], v[162:165], v[190:193], v[118:121]
	v_mfma_f32_16x16x32_bf16 v[118:121], v[166:169], v[194:197], v[118:121]
	v_mfma_f32_16x16x32_bf16 v[114:117], v[182:185], v[190:193], v[114:117]
	v_mfma_f32_16x16x32_bf16 v[114:117], v[186:189], v[194:197], v[114:117]
	v_mfma_f32_16x16x32_bf16 v[102:105], v[162:165], v[198:201], v[102:105]
	v_mfma_f32_16x16x32_bf16 v[102:105], v[166:169], v[204:207], v[102:105]
	v_mfma_f32_16x16x32_bf16 v[98:101], v[182:185], v[198:201], v[98:101]
	v_mfma_f32_16x16x32_bf16 v[98:101], v[186:189], v[204:207], v[98:101]
	v_mfma_f32_16x16x32_bf16 v[86:89], v[162:165], v[208:211], v[86:89]
	v_mfma_f32_16x16x32_bf16 v[86:89], v[166:169], v[212:215], v[86:89]
	v_mfma_f32_16x16x32_bf16 v[82:85], v[182:185], v[208:211], v[82:85]
	v_mfma_f32_16x16x32_bf16 v[82:85], v[186:189], v[212:215], v[82:85]
	v_mfma_f32_16x16x32_bf16 v[70:73], v[162:165], v[216:219], v[70:73]
	v_mfma_f32_16x16x32_bf16 v[70:73], v[166:169], v[220:223], v[70:73]
	v_mfma_f32_16x16x32_bf16 v[66:69], v[182:185], v[216:219], v[66:69]
	v_mfma_f32_16x16x32_bf16 v[66:69], v[186:189], v[220:223], v[66:69]
	s_setprio 0
	s_barrier
	s_add_i32 s71, s71, s6
	v_lshl_add_u64 v[224:225], s[42:43], 0, v[134:135]
	s_mov_b32 m0, s71
	ds_read_b128 v[190:193], v177 offset:16384
	ds_read_b128 v[194:197], v177 offset:17408
	ds_read_b128 v[198:201], v177 offset:18432
	ds_read_b128 v[204:207], v177 offset:19456
	ds_read_b128 v[208:211], v177 offset:20480
	ds_read_b128 v[212:215], v177 offset:21504
	ds_read_b128 v[216:219], v177 offset:22528
	ds_read_b128 v[220:223], v177 offset:23552
	global_load_lds_dwordx4 v[224:225], off
	s_add_i32 m0, s71, 0x2000
	s_add_u32 s84, s42, 0x10000
	v_lshl_add_u64 v[226:227], s[42:43], 0, v[138:139]
	s_addc_u32 s85, s43, 0
	s_add_i32 s71, s74, s6
	global_load_lds_dwordx4 v[226:227], off
	v_lshl_add_u64 v[228:229], s[84:85], 0, v[134:135]
	s_mov_b32 m0, s71
	v_lshl_add_u64 v[230:231], s[44:45], 0, v[136:137]
	global_load_lds_dwordx4 v[228:229], off
	v_lshl_add_u64 v[228:229], s[84:85], 0, v[138:139]
	s_add_i32 m0, s71, 0x2000
	s_nop 0
	global_load_lds_dwordx4 v[228:229], off
	v_lshl_add_u64 v[228:229], s[44:45], 0, v[132:133]
	s_mov_b32 m0, s7
	s_nop 0
	global_load_lds_dwordx4 v[228:229], off
	s_mov_b32 m0, s57
	s_nop 0
	global_load_lds_dwordx4 v[230:231], off
	s_waitcnt vmcnt(8)
	s_waitcnt lgkmcnt(0)
	s_barrier
; #define PG8_STAGE(bufoff, gbase, voff) do { _Pragma("unroll") for (int _i = 0; _i < 2; ++_i) \
;         __builtin_amdgcn_global_load_lds((const unsigned*)((const char*)(gbase) + (voff)[_i]), (PG8_LAS unsigned*)(lds + (bufoff) + ldsw + _i * 8192), 16, 0, 0); } while (0)
; #define PG8_LDA(dst, b, h) do { _Pragma("unroll") for (int m = 0; m < 4; ++m) _Pragma("unroll") for (int k = 0; k < 2; ++k) dst[m][k] = *(const PG8_LAS bf16x8*)(lds + PG8_SA(b, h) + aoff + m * 2048 + k * 1024); } while (0)
; #define PG8_LDB(dst, b, h) do { _Pragma("unroll") for (int n = 0; n < 2; ++n) _Pragma("unroll") for (int k = 0; k < 2; ++k) dst[n][k] = *(const PG8_LAS bf16x8*)(lds + PG8_SB(b, h) + boff + n * 2048 + k * 1024); } while (0)
; #define PG8_MMA(ai, bj, At, Bt) do { __builtin_amdgcn_s_setprio(1); _Pragma("unroll") for (int m = 0; m < 4; ++m) _Pragma("unroll") for (int n = 0; n < 2; ++n) _Pragma("unroll") for (int k = 0; k < 2; ++k) \
;         acc[ai][bj][m][n] = __builtin_amdgcn_mfma_f32_16x16x32_bf16(Bt[n][k], At[m][k], acc[ai][bj][m][n], 0, 0, 0); __builtin_amdgcn_s_setprio(0); } while (0)
; #define PG8_WAIT_V(n) asm volatile("s_waitcnt vmcnt(" #n ")" ::: "memory")
; #define PG8_WAIT_L(n) asm volatile("s_waitcnt lgkmcnt(" #n ")" ::: "memory")
; #define PG8_BAR __builtin_amdgcn_s_barrier()
; #define PG8_SCHED __builtin_amdgcn_sched_barrier(0)
; template <class Epi, class Sched, bool ALIGN_EPI = false, bool SP2 = false>
; __device__ __forceinline__ void gemm_phase(PG8_LAS unsigned char* lds, const Gemm g, const Sched& S, const Epi& E, const int wave_s) {
;     ...
;             PG8_WAIT_V(8); PG8_WAIT_L(0); PG8_BAR; PG8_MMA(1, 0, At, B0); PG8_MMA(1, 1, At, B1); PG8_BAR; PG8_SCHED;
;             PG8_LDB(B0, 1, 0); PG8_LDB(B1, 1, 1); PG8_SCHED; PG8_LDA(At, 1, 0); PG8_STAGE(PG8_SA(0, 1), a2 + hstep, voffA);
;             PG8_WAIT_V(8); PG8_WAIT_L(0); PG8_BAR; PG8_MMA(0, 0, At, B0); PG8_MMA(0, 1, At, B1); PG8_BAR; PG8_SCHED;
	s_setprio 1
	s_waitcnt lgkmcnt(0)
	v_mfma_f32_16x16x32_bf16 v[62:65], v[146:149], v[190:193], v[62:65]
	v_mfma_f32_16x16x32_bf16 v[62:65], v[150:153], v[194:197], v[62:65]
	v_mfma_f32_16x16x32_bf16 v[58:61], v[154:157], v[190:193], v[58:61]
	v_mfma_f32_16x16x32_bf16 v[58:61], v[158:161], v[194:197], v[58:61]
	v_mfma_f32_16x16x32_bf16 v[46:49], v[146:149], v[198:201], v[46:49]
	v_mfma_f32_16x16x32_bf16 v[46:49], v[150:153], v[204:207], v[46:49]
	v_mfma_f32_16x16x32_bf16 v[42:45], v[154:157], v[198:201], v[42:45]
	v_mfma_f32_16x16x32_bf16 v[42:45], v[158:161], v[204:207], v[42:45]
	v_mfma_f32_16x16x32_bf16 v[30:33], v[146:149], v[208:211], v[30:33]
	v_mfma_f32_16x16x32_bf16 v[30:33], v[150:153], v[212:215], v[30:33]
	v_mfma_f32_16x16x32_bf16 v[26:29], v[154:157], v[208:211], v[26:29]
	v_mfma_f32_16x16x32_bf16 v[26:29], v[158:161], v[212:215], v[26:29]
	v_mfma_f32_16x16x32_bf16 v[14:17], v[146:149], v[216:219], v[14:17]
	v_mfma_f32_16x16x32_bf16 v[14:17], v[150:153], v[220:223], v[14:17]
	v_mfma_f32_16x16x32_bf16 v[10:13], v[154:157], v[216:219], v[10:13]
	v_mfma_f32_16x16x32_bf16 v[10:13], v[158:161], v[220:223], v[10:13]
	s_setprio 0
	s_setprio 1
	v_mfma_f32_16x16x32_bf16 v[54:57], v[162:165], v[190:193], v[54:57]
	v_mfma_f32_16x16x32_bf16 v[54:57], v[166:169], v[194:197], v[54:57]
	v_mfma_f32_16x16x32_bf16 v[50:53], v[182:185], v[190:193], v[50:53]
	v_mfma_f32_16x16x32_bf16 v[50:53], v[186:189], v[194:197], v[50:53]
	v_mfma_f32_16x16x32_bf16 v[38:41], v[162:165], v[198:201], v[38:41]
	v_mfma_f32_16x16x32_bf16 v[38:41], v[166:169], v[204:207], v[38:41]
	v_mfma_f32_16x16x32_bf16 v[34:37], v[182:185], v[198:201], v[34:37]
	v_mfma_f32_16x16x32_bf16 v[34:37], v[186:189], v[204:207], v[34:37]
	v_mfma_f32_16x16x32_bf16 v[22:25], v[162:165], v[208:211], v[22:25]
	v_mfma_f32_16x16x32_bf16 v[22:25], v[166:169], v[212:215], v[22:25]
	v_mfma_f32_16x16x32_bf16 v[18:21], v[182:185], v[208:211], v[18:21]
	v_mfma_f32_16x16x32_bf16 v[18:21], v[186:189], v[212:215], v[18:21]
	v_mfma_f32_16x16x32_bf16 v[6:9], v[162:165], v[216:219], v[6:9]
	v_mfma_f32_16x16x32_bf16 v[6:9], v[166:169], v[220:223], v[6:9]
	v_mfma_f32_16x16x32_bf16 v[2:5], v[182:185], v[216:219], v[2:5]
	v_mfma_f32_16x16x32_bf16 v[2:5], v[186:189], v[220:223], v[2:5]
	s_setprio 0
	s_barrier
	s_add_i32 s71, 0, 0x18000
	v_add_u32_e32 v0, s71, v171
	s_add_i32 s74, 0, 0x1c000
	ds_read_b128 v[146:149], v0
	ds_read_b128 v[150:153], v0 offset:1024
	ds_read_b128 v[154:157], v0 offset:2048
	ds_read_b128 v[158:161], v0 offset:3072
	v_add_u32_e32 v0, s74, v171
	ds_read_b128 v[162:165], v0
	ds_read_b128 v[166:169], v0 offset:1024
	ds_read_b128 v[182:185], v0 offset:2048
	ds_read_b128 v[186:189], v0 offset:3072
	s_add_u32 s44, s44, 0x40000
	s_addc_u32 s45, s45, 0
	s_mov_b32 m0, s8
	v_lshl_add_u64 v[232:233], s[44:45], 0, v[132:133]
	ds_read_b128 v[190:193], v177 offset:32768
	ds_read_b128 v[194:197], v177 offset:33792
	ds_read_b128 v[198:201], v177 offset:34816
	ds_read_b128 v[204:207], v177 offset:35840
	ds_read_b128 v[208:211], v177 offset:36864
	ds_read_b128 v[212:215], v177 offset:37888
	ds_read_b128 v[216:219], v177 offset:38912
	ds_read_b128 v[220:223], v177 offset:39936
	global_load_lds_dwordx4 v[232:233], off
	v_lshl_add_u64 v[232:233], s[44:45], 0, v[136:137]
	s_mov_b32 m0, s9
	s_nop 0
	global_load_lds_dwordx4 v[232:233], off
	s_waitcnt vmcnt(8)
	s_waitcnt lgkmcnt(0)
	s_barrier
	s_setprio 1
	s_waitcnt lgkmcnt(0)
	v_mfma_f32_16x16x32_bf16 v[126:129], v[146:149], v[190:193], v[126:129]
	v_mfma_f32_16x16x32_bf16 v[126:129], v[150:153], v[194:197], v[126:129]
	v_mfma_f32_16x16x32_bf16 v[122:125], v[154:157], v[190:193], v[122:125]
	v_mfma_f32_16x16x32_bf16 v[122:125], v[158:161], v[194:197], v[122:125]
	v_mfma_f32_16x16x32_bf16 v[110:113], v[146:149], v[198:201], v[110:113]
	v_mfma_f32_16x16x32_bf16 v[110:113], v[150:153], v[204:207], v[110:113]
	v_mfma_f32_16x16x32_bf16 v[106:109], v[154:157], v[198:201], v[106:109]
	v_mfma_f32_16x16x32_bf16 v[106:109], v[158:161], v[204:207], v[106:109]
	v_mfma_f32_16x16x32_bf16 v[94:97], v[146:149], v[208:211], v[94:97]
	v_mfma_f32_16x16x32_bf16 v[94:97], v[150:153], v[212:215], v[94:97]
	v_mfma_f32_16x16x32_bf16 v[90:93], v[154:157], v[208:211], v[90:93]
	v_mfma_f32_16x16x32_bf16 v[90:93], v[158:161], v[212:215], v[90:93]
	v_mfma_f32_16x16x32_bf16 v[78:81], v[146:149], v[216:219], v[78:81]
	v_mfma_f32_16x16x32_bf16 v[78:81], v[150:153], v[220:223], v[78:81]
	v_mfma_f32_16x16x32_bf16 v[74:77], v[154:157], v[216:219], v[74:77]
	v_mfma_f32_16x16x32_bf16 v[74:77], v[158:161], v[220:223], v[74:77]
	s_setprio 0
	s_setprio 1
	v_mfma_f32_16x16x32_bf16 v[118:121], v[162:165], v[190:193], v[118:121]
	v_mfma_f32_16x16x32_bf16 v[118:121], v[166:169], v[194:197], v[118:121]
	v_mfma_f32_16x16x32_bf16 v[114:117], v[182:185], v[190:193], v[114:117]
	v_mfma_f32_16x16x32_bf16 v[114:117], v[186:189], v[194:197], v[114:117]
	v_mfma_f32_16x16x32_bf16 v[102:105], v[162:165], v[198:201], v[102:105]
	v_mfma_f32_16x16x32_bf16 v[102:105], v[166:169], v[204:207], v[102:105]
	v_mfma_f32_16x16x32_bf16 v[98:101], v[182:185], v[198:201], v[98:101]
	v_mfma_f32_16x16x32_bf16 v[98:101], v[186:189], v[204:207], v[98:101]
	v_mfma_f32_16x16x32_bf16 v[86:89], v[162:165], v[208:211], v[86:89]
	v_mfma_f32_16x16x32_bf16 v[86:89], v[166:169], v[212:215], v[86:89]
	v_mfma_f32_16x16x32_bf16 v[82:85], v[182:185], v[208:211], v[82:85]
	v_mfma_f32_16x16x32_bf16 v[82:85], v[186:189], v[212:215], v[82:85]
	v_mfma_f32_16x16x32_bf16 v[70:73], v[162:165], v[216:219], v[70:73]
	v_mfma_f32_16x16x32_bf16 v[70:73], v[166:169], v[220:223], v[70:73]
	v_mfma_f32_16x16x32_bf16 v[66:69], v[182:185], v[216:219], v[66:69]
	v_mfma_f32_16x16x32_bf16 v[66:69], v[186:189], v[220:223], v[66:69]
	s_setprio 0
	s_barrier
; #define PG8_STAGE(bufoff, gbase, voff) do { _Pragma("unroll") for (int _i = 0; _i < 2; ++_i) \
;         __builtin_amdgcn_global_load_lds((const unsigned*)((const char*)(gbase) + (voff)[_i]), (PG8_LAS unsigned*)(lds + (bufoff) + ldsw + _i * 8192), 16, 0, 0); } while (0)
; #define PG8_LDA(dst, b, h) do { _Pragma("unroll") for (int m = 0; m < 4; ++m) _Pragma("unroll") for (int k = 0; k < 2; ++k) dst[m][k] = *(const PG8_LAS bf16x8*)(lds + PG8_SA(b, h) + aoff + m * 2048 + k * 1024); } while (0)
; #define PG8_MMA(ai, bj, At, Bt) do { __builtin_amdgcn_s_setprio(1); _Pragma("unroll") for (int m = 0; m < 4; ++m) _Pragma("unroll") for (int n = 0; n < 2; ++n) _Pragma("unroll") for (int k = 0; k < 2; ++k) \
;         acc[ai][bj][m][n] = __builtin_amdgcn_mfma_f32_16x16x32_bf16(Bt[n][k], At[m][k], acc[ai][bj][m][n], 0, 0, 0); __builtin_amdgcn_s_setprio(0); } while (0)
; #define PG8_WAIT_V(n) asm volatile("s_waitcnt vmcnt(" #n ")" ::: "memory")
; #define PG8_WAIT_L(n) asm volatile("s_waitcnt lgkmcnt(" #n ")" ::: "memory")
; #define PG8_BAR __builtin_amdgcn_s_barrier()
; #define PG8_SCHED __builtin_amdgcn_sched_barrier(0)
; template <class Epi, class Sched, bool ALIGN_EPI = false, bool SP2 = false>
; __device__ __forceinline__ void gemm_phase(PG8_LAS unsigned char* lds, const Gemm g, const Sched& S, const Epi& E, const int wave_s) {
;     ...
;             PG8_LDA(At, 1, 1); PG8_STAGE(PG8_SB(1, 0), b3, voffB); PG8_STAGE(PG8_SB(1, 1), b3 + bhstep, voffB); PG8_STAGE(PG8_SA(1, 0), a3, voffA);
;             PG8_WAIT_V(8); PG8_WAIT_L(0); PG8_BAR; PG8_MMA(1, 0, At, B0); PG8_MMA(1, 1, At, B1); PG8_BAR; PG8_SCHED;
	s_add_i32 s44, s71, s6
	v_lshl_add_u64 v[224:225], v[224:225], 0, s[24:25]
	s_mov_b32 m0, s44
	ds_read_b128 v[190:193], v177 offset:49152
	ds_read_b128 v[194:197], v177 offset:50176
	ds_read_b128 v[198:201], v177 offset:51200
	ds_read_b128 v[204:207], v177 offset:52224
	ds_read_b128 v[208:211], v177 offset:53248
	ds_read_b128 v[212:215], v177 offset:54272
	ds_read_b128 v[216:219], v177 offset:55296
	ds_read_b128 v[220:223], v177 offset:56320
	global_load_lds_dwordx4 v[224:225], off
	s_add_i32 m0, s44, 0x2000
	s_add_u32 s42, s42, 0x10080
	v_lshl_add_u64 v[224:225], v[226:227], 0, s[24:25]
	s_addc_u32 s43, s43, 0
	s_add_i32 s44, s74, s6
	global_load_lds_dwordx4 v[224:225], off
	v_lshl_add_u64 v[224:225], s[42:43], 0, v[134:135]
	s_mov_b32 m0, s44
	s_nop 0
	global_load_lds_dwordx4 v[224:225], off
	v_lshl_add_u64 v[224:225], s[42:43], 0, v[138:139]
	s_add_i32 m0, s44, 0x2000
	s_nop 0
	global_load_lds_dwordx4 v[224:225], off
	v_lshl_add_u64 v[224:225], v[228:229], 0, s[24:25]
	s_mov_b32 m0, s11
	s_nop 0
	global_load_lds_dwordx4 v[224:225], off
	v_lshl_add_u64 v[224:225], v[230:231], 0, s[24:25]
	s_mov_b32 m0, s12
	s_nop 0
	global_load_lds_dwordx4 v[224:225], off
	s_waitcnt vmcnt(8)
	s_waitcnt lgkmcnt(0)
	s_barrier
	s_setprio 1
	s_waitcnt lgkmcnt(0)
	v_mfma_f32_16x16x32_bf16 v[62:65], v[146:149], v[190:193], v[62:65]
	v_mfma_f32_16x16x32_bf16 v[62:65], v[150:153], v[194:197], v[62:65]
	v_mfma_f32_16x16x32_bf16 v[58:61], v[154:157], v[190:193], v[58:61]
	v_mfma_f32_16x16x32_bf16 v[58:61], v[158:161], v[194:197], v[58:61]
	v_mfma_f32_16x16x32_bf16 v[46:49], v[146:149], v[198:201], v[46:49]
	v_mfma_f32_16x16x32_bf16 v[46:49], v[150:153], v[204:207], v[46:49]
	v_mfma_f32_16x16x32_bf16 v[42:45], v[154:157], v[198:201], v[42:45]
	v_mfma_f32_16x16x32_bf16 v[42:45], v[158:161], v[204:207], v[42:45]
	v_mfma_f32_16x16x32_bf16 v[30:33], v[146:149], v[208:211], v[30:33]
	v_mfma_f32_16x16x32_bf16 v[30:33], v[150:153], v[212:215], v[30:33]
	v_mfma_f32_16x16x32_bf16 v[26:29], v[154:157], v[208:211], v[26:29]
	v_mfma_f32_16x16x32_bf16 v[26:29], v[158:161], v[212:215], v[26:29]
	v_mfma_f32_16x16x32_bf16 v[14:17], v[146:149], v[216:219], v[14:17]
	v_mfma_f32_16x16x32_bf16 v[14:17], v[150:153], v[220:223], v[14:17]
	v_mfma_f32_16x16x32_bf16 v[10:13], v[154:157], v[216:219], v[10:13]
	v_mfma_f32_16x16x32_bf16 v[10:13], v[158:161], v[220:223], v[10:13]
	s_setprio 0
	s_setprio 1
	v_mfma_f32_16x16x32_bf16 v[54:57], v[162:165], v[190:193], v[54:57]
	v_mfma_f32_16x16x32_bf16 v[54:57], v[166:169], v[194:197], v[54:57]
	v_mfma_f32_16x16x32_bf16 v[50:53], v[182:185], v[190:193], v[50:53]
	v_mfma_f32_16x16x32_bf16 v[50:53], v[186:189], v[194:197], v[50:53]
	v_mfma_f32_16x16x32_bf16 v[38:41], v[162:165], v[198:201], v[38:41]
	v_mfma_f32_16x16x32_bf16 v[38:41], v[166:169], v[204:207], v[38:41]
	v_mfma_f32_16x16x32_bf16 v[34:37], v[182:185], v[198:201], v[34:37]
	v_mfma_f32_16x16x32_bf16 v[34:37], v[186:189], v[204:207], v[34:37]
	v_mfma_f32_16x16x32_bf16 v[22:25], v[162:165], v[208:211], v[22:25]
	v_mfma_f32_16x16x32_bf16 v[22:25], v[166:169], v[212:215], v[22:25]
	v_mfma_f32_16x16x32_bf16 v[18:21], v[182:185], v[208:211], v[18:21]
	v_mfma_f32_16x16x32_bf16 v[18:21], v[186:189], v[212:215], v[18:21]
	v_mfma_f32_16x16x32_bf16 v[6:9], v[162:165], v[216:219], v[6:9]
	v_mfma_f32_16x16x32_bf16 v[6:9], v[166:169], v[220:223], v[6:9]
	v_mfma_f32_16x16x32_bf16 v[2:5], v[182:185], v[216:219], v[2:5]
	v_mfma_f32_16x16x32_bf16 v[2:5], v[186:189], v[220:223], v[2:5]
	s_setprio 0
	s_barrier
	s_add_i32 s70, s70, 2
	s_add_u32 s20, s20, 0x100
	s_addc_u32 s21, s21, 0
	s_add_u32 s68, s68, 0x100
	s_addc_u32 s69, s69, 0
	s_cmp_gt_u32 s70, 13
	s_cbranch_scc0 .LBB0_136
	s_and_b64 vcc, exec, s[60:61]
	s_cbranch_vccz .LBB0_139
	s_barrier

; #define PG8_STAGE(bufoff, gbase, voff) do { _Pragma("unroll") for (int _i = 0; _i < 2; ++_i) \
;         __builtin_amdgcn_global_load_lds((const unsigned*)((const char*)(gbase) + (voff)[_i]), (PG8_LAS unsigned*)(lds + (bufoff) + ldsw + _i * 8192), 16, 0, 0); } while (0)
; #define PG8_LDA(dst, b, h) do { _Pragma("unroll") for (int m = 0; m < 4; ++m) _Pragma("unroll") for (int k = 0; k < 2; ++k) dst[m][k] = *(const PG8_LAS bf16x8*)(lds + PG8_SA(b, h) + aoff + m * 2048 + k * 1024); } while (0)
; #define PG8_LDB(dst, b, h) do { _Pragma("unroll") for (int n = 0; n < 2; ++n) _Pragma("unroll") for (int k = 0; k < 2; ++k) dst[n][k] = *(const PG8_LAS bf16x8*)(lds + PG8_SB(b, h) + boff + n * 2048 + k * 1024); } while (0)
; #define PG8_MMA(ai, bj, At, Bt) do { __builtin_amdgcn_s_setprio(1); _Pragma("unroll") for (int m = 0; m < 4; ++m) _Pragma("unroll") for (int n = 0; n < 2; ++n) _Pragma("unroll") for (int k = 0; k < 2; ++k) \
;         acc[ai][bj][m][n] = __builtin_amdgcn_mfma_f32_16x16x32_bf16(Bt[n][k], At[m][k], acc[ai][bj][m][n], 0, 0, 0); __builtin_amdgcn_s_setprio(0); } while (0)
; #define PG8_WAIT_V(n) asm volatile("s_waitcnt vmcnt(" #n ")" ::: "memory")
; #define PG8_WAIT_L(n) asm volatile("s_waitcnt lgkmcnt(" #n ")" ::: "memory")
; template <class Epi, class Sched, bool ALIGN_EPI = false, bool SP2 = false>
; __device__ __forceinline__ void gemm_phase(PG8_LAS unsigned char* lds, const Gemm g, const Sched& S, const Epi& E, const int wave_s) {
;     ...
;             const bool last = (t == nt - 2);
;             const char* a1 = cA + (size_t)(t + 1) * kstep;
;             const char* a2 = last ? nA : cA + (size_t)(t + 2) * kstep; const char* b2 = last ? nB : cB + (size_t)(t + 2) * kstep;
;             const char* a3 = a2 + kstep; const char* b3 = b2 + kstep;
;             if (last && has_next) S.a_ready(nxt);
;             if constexpr (SP2) {
;             PG8_LDB(B0, 0, 0); PG8_LDB(B1, 0, 1); PG8_SCHED; PG8_LDA(At, 0, 0); PG8_STAGE(PG8_SA(1, 1), a1 + hstep, voffA);
;             PG8_WAIT_V(8); PG8_WAIT_L(0); PG8_BAR; PG8_MMA(0, 0, At, B0); PG8_MMA(0, 1, At, B1); PG8_BAR; PG8_SCHED;
;             PG8_LDA(At, 0, 1); PG8_STAGE(PG8_SB(0, 0), b2, voffB); PG8_STAGE(PG8_SB(0, 1), b2 + bhstep, voffB); PG8_STAGE(PG8_SA(0, 0), a2, voffA);
;             PG8_WAIT_V(8); PG8_WAIT_L(0); PG8_BAR; PG8_MMA(1, 0, At, B0); PG8_MMA(1, 1, At, B1); PG8_BAR; PG8_SCHED;
.LBB0_753:
	s_add_i32 s54, s48, 2
	s_add_u32 s55, s44, 0x80
	s_addc_u32 s49, s45, 0
	s_add_i32 s60, 0, 0x10000
	s_cmp_eq_u32 s16, s48
	s_cselect_b32 s49, s39, s49
	s_cselect_b32 s48, s47, s55
	s_cselect_b32 s57, s29, s53
	s_cselect_b32 s56, s51, s52
	s_add_i32 s55, 0, 0x14000
	v_add_u32_e32 v142, s60, v205
	v_add_u32_e32 v160, s55, v205
	ds_read_b128 v[130:133], v142
	ds_read_b128 v[134:137], v142 offset:1024
	ds_read_b128 v[138:141], v142 offset:2048
	ds_read_b128 v[142:145], v142 offset:3072
	ds_read_b128 v[146:149], v160
	ds_read_b128 v[150:153], v160 offset:1024
	ds_read_b128 v[154:157], v160 offset:2048
	ds_read_b128 v[160:163], v160 offset:3072
	v_lshl_add_u64 v[220:221], s[44:45], 0, v[178:179]
	s_add_i32 m0, s7, 0xc000
	ds_read_b128 v[164:167], v208
	ds_read_b128 v[182:185], v208 offset:1024
	ds_read_b128 v[186:189], v208 offset:2048
	ds_read_b128 v[190:193], v208 offset:3072
	ds_read_b128 v[194:197], v208 offset:4096
	ds_read_b128 v[198:201], v208 offset:5120
	ds_read_b128 v[212:215], v208 offset:6144
	ds_read_b128 v[216:219], v208 offset:7168
	global_load_lds_dwordx4 v[220:221], off
	v_lshl_add_u64 v[220:221], s[44:45], 0, v[180:181]
	s_add_i32 m0, s7, 0xe000
	s_nop 0
	global_load_lds_dwordx4 v[220:221], off
	s_waitcnt vmcnt(8)
	s_waitcnt lgkmcnt(0)
	s_barrier
	s_setprio 1
	s_waitcnt lgkmcnt(0)
	v_mfma_f32_16x16x32_bf16 v[126:129], v[130:133], v[164:167], v[126:129]
	v_mfma_f32_16x16x32_bf16 v[126:129], v[134:137], v[182:185], v[126:129]
	v_mfma_f32_16x16x32_bf16 v[122:125], v[138:141], v[164:167], v[122:125]
	v_mfma_f32_16x16x32_bf16 v[122:125], v[142:145], v[182:185], v[122:125]
	v_mfma_f32_16x16x32_bf16 v[110:113], v[130:133], v[186:189], v[110:113]
	v_mfma_f32_16x16x32_bf16 v[110:113], v[134:137], v[190:193], v[110:113]
	v_mfma_f32_16x16x32_bf16 v[106:109], v[138:141], v[186:189], v[106:109]
	v_mfma_f32_16x16x32_bf16 v[106:109], v[142:145], v[190:193], v[106:109]
	v_mfma_f32_16x16x32_bf16 v[94:97], v[130:133], v[194:197], v[94:97]
	v_mfma_f32_16x16x32_bf16 v[94:97], v[134:137], v[198:201], v[94:97]
	v_mfma_f32_16x16x32_bf16 v[90:93], v[138:141], v[194:197], v[90:93]
	v_mfma_f32_16x16x32_bf16 v[90:93], v[142:145], v[198:201], v[90:93]
	v_mfma_f32_16x16x32_bf16 v[78:81], v[130:133], v[212:215], v[78:81]
	v_mfma_f32_16x16x32_bf16 v[78:81], v[134:137], v[216:219], v[78:81]
	v_mfma_f32_16x16x32_bf16 v[74:77], v[138:141], v[212:215], v[74:77]
	v_mfma_f32_16x16x32_bf16 v[74:77], v[142:145], v[216:219], v[74:77]
	s_setprio 0
	s_setprio 1
	v_mfma_f32_16x16x32_bf16 v[118:121], v[146:149], v[164:167], v[118:121]
	v_mfma_f32_16x16x32_bf16 v[118:121], v[150:153], v[182:185], v[118:121]
	v_mfma_f32_16x16x32_bf16 v[114:117], v[154:157], v[164:167], v[114:117]
	v_mfma_f32_16x16x32_bf16 v[114:117], v[160:163], v[182:185], v[114:117]
	v_mfma_f32_16x16x32_bf16 v[102:105], v[146:149], v[186:189], v[102:105]
	v_mfma_f32_16x16x32_bf16 v[102:105], v[150:153], v[190:193], v[102:105]
	v_mfma_f32_16x16x32_bf16 v[98:101], v[154:157], v[186:189], v[98:101]
	v_mfma_f32_16x16x32_bf16 v[98:101], v[160:163], v[190:193], v[98:101]
	v_mfma_f32_16x16x32_bf16 v[86:89], v[146:149], v[194:197], v[86:89]
	v_mfma_f32_16x16x32_bf16 v[86:89], v[150:153], v[198:201], v[86:89]
	v_mfma_f32_16x16x32_bf16 v[82:85], v[154:157], v[194:197], v[82:85]
	v_mfma_f32_16x16x32_bf16 v[82:85], v[160:163], v[198:201], v[82:85]
	v_mfma_f32_16x16x32_bf16 v[70:73], v[146:149], v[212:215], v[70:73]
	v_mfma_f32_16x16x32_bf16 v[70:73], v[150:153], v[216:219], v[70:73]
	v_mfma_f32_16x16x32_bf16 v[66:69], v[154:157], v[212:215], v[66:69]
	v_mfma_f32_16x16x32_bf16 v[66:69], v[160:163], v[216:219], v[66:69]
	s_setprio 0
	s_barrier
	s_add_i32 s60, s60, s5
	v_lshl_add_u64 v[220:221], s[56:57], 0, v[170:171]
	s_mov_b32 m0, s60
	ds_read_b128 v[164:167], v208 offset:16384
	ds_read_b128 v[182:185], v208 offset:17408
	ds_read_b128 v[186:189], v208 offset:18432
	ds_read_b128 v[190:193], v208 offset:19456
	ds_read_b128 v[194:197], v208 offset:20480
	ds_read_b128 v[198:201], v208 offset:21504
	ds_read_b128 v[212:215], v208 offset:22528
	ds_read_b128 v[216:219], v208 offset:23552
	global_load_lds_dwordx4 v[220:221], off
	s_add_i32 m0, s60, 0x2000
	v_lshl_add_u64 v[222:223], s[56:57], 0, v[158:159]
	s_add_u32 s56, s56, s4
	s_addc_u32 s57, s57, 0
	s_add_i32 s55, s55, s5
	global_load_lds_dwordx4 v[222:223], off
	v_lshl_add_u64 v[224:225], s[56:57], 0, v[170:171]
	s_mov_b32 m0, s55
	v_lshl_add_u64 v[226:227], s[56:57], 0, v[158:159]
	global_load_lds_dwordx4 v[224:225], off
	s_add_i32 m0, s55, 0x2000
	v_lshl_add_u64 v[228:229], s[48:49], 0, v[172:173]
	global_load_lds_dwordx4 v[226:227], off
	s_mov_b32 m0, s7
	v_lshl_add_u64 v[230:231], s[48:49], 0, v[168:169]
	global_load_lds_dwordx4 v[228:229], off
	s_mov_b32 m0, s8
	s_nop 0
	global_load_lds_dwordx4 v[230:231], off
	s_waitcnt vmcnt(8)
	s_waitcnt lgkmcnt(0)
	s_barrier
; #define PG8_STAGE(bufoff, gbase, voff) do { _Pragma("unroll") for (int _i = 0; _i < 2; ++_i) \
;         __builtin_amdgcn_global_load_lds((const unsigned*)((const char*)(gbase) + (voff)[_i]), (PG8_LAS unsigned*)(lds + (bufoff) + ldsw + _i * 8192), 16, 0, 0); } while (0)
; #define PG8_LDA(dst, b, h) do { _Pragma("unroll") for (int m = 0; m < 4; ++m) _Pragma("unroll") for (int k = 0; k < 2; ++k) dst[m][k] = *(const PG8_LAS bf16x8*)(lds + PG8_SA(b, h) + aoff + m * 2048 + k * 1024); } while (0)
; #define PG8_LDB(dst, b, h) do { _Pragma("unroll") for (int n = 0; n < 2; ++n) _Pragma("unroll") for (int k = 0; k < 2; ++k) dst[n][k] = *(const PG8_LAS bf16x8*)(lds + PG8_SB(b, h) + boff + n * 2048 + k * 1024); } while (0)
; #define PG8_MMA(ai, bj, At, Bt) do { __builtin_amdgcn_s_setprio(1); _Pragma("unroll") for (int m = 0; m < 4; ++m) _Pragma("unroll") for (int n = 0; n < 2; ++n) _Pragma("unroll") for (int k = 0; k < 2; ++k) \
;         acc[ai][bj][m][n] = __builtin_amdgcn_mfma_f32_16x16x32_bf16(Bt[n][k], At[m][k], acc[ai][bj][m][n], 0, 0, 0); __builtin_amdgcn_s_setprio(0); } while (0)
; #define PG8_WAIT_V(n) asm volatile("s_waitcnt vmcnt(" #n ")" ::: "memory")
; #define PG8_WAIT_L(n) asm volatile("s_waitcnt lgkmcnt(" #n ")" ::: "memory")
; #define PG8_BAR __builtin_amdgcn_s_barrier()
; #define PG8_SCHED __builtin_amdgcn_sched_barrier(0)
; template <class Epi, class Sched, bool ALIGN_EPI = false, bool SP2 = false>
; __device__ __forceinline__ void gemm_phase(PG8_LAS unsigned char* lds, const Gemm g, const Sched& S, const Epi& E, const int wave_s) {
;     ...
;             PG8_WAIT_V(8); PG8_WAIT_L(0); PG8_BAR; PG8_MMA(1, 0, At, B0); PG8_MMA(1, 1, At, B1); PG8_BAR; PG8_SCHED;
;             PG8_LDB(B0, 1, 0); PG8_LDB(B1, 1, 1); PG8_SCHED; PG8_LDA(At, 1, 0); PG8_STAGE(PG8_SA(0, 1), a2 + hstep, voffA);
;             PG8_WAIT_V(8); PG8_WAIT_L(0); PG8_BAR; PG8_MMA(0, 0, At, B0); PG8_MMA(0, 1, At, B1); PG8_BAR; PG8_SCHED;
	s_setprio 1
	s_waitcnt lgkmcnt(0)
	v_mfma_f32_16x16x32_bf16 v[62:65], v[130:133], v[164:167], v[62:65]
	v_mfma_f32_16x16x32_bf16 v[62:65], v[134:137], v[182:185], v[62:65]
	v_mfma_f32_16x16x32_bf16 v[58:61], v[138:141], v[164:167], v[58:61]
	v_mfma_f32_16x16x32_bf16 v[58:61], v[142:145], v[182:185], v[58:61]
	v_mfma_f32_16x16x32_bf16 v[46:49], v[130:133], v[186:189], v[46:49]
	v_mfma_f32_16x16x32_bf16 v[46:49], v[134:137], v[190:193], v[46:49]
	v_mfma_f32_16x16x32_bf16 v[42:45], v[138:141], v[186:189], v[42:45]
	v_mfma_f32_16x16x32_bf16 v[42:45], v[142:145], v[190:193], v[42:45]
	v_mfma_f32_16x16x32_bf16 v[30:33], v[130:133], v[194:197], v[30:33]
	v_mfma_f32_16x16x32_bf16 v[30:33], v[134:137], v[198:201], v[30:33]
	v_mfma_f32_16x16x32_bf16 v[26:29], v[138:141], v[194:197], v[26:29]
	v_mfma_f32_16x16x32_bf16 v[26:29], v[142:145], v[198:201], v[26:29]
	v_mfma_f32_16x16x32_bf16 v[14:17], v[130:133], v[212:215], v[14:17]
	v_mfma_f32_16x16x32_bf16 v[14:17], v[134:137], v[216:219], v[14:17]
	v_mfma_f32_16x16x32_bf16 v[10:13], v[138:141], v[212:215], v[10:13]
	v_mfma_f32_16x16x32_bf16 v[10:13], v[142:145], v[216:219], v[10:13]
	s_setprio 0
	s_setprio 1
	v_mfma_f32_16x16x32_bf16 v[54:57], v[146:149], v[164:167], v[54:57]
	v_mfma_f32_16x16x32_bf16 v[54:57], v[150:153], v[182:185], v[54:57]
	v_mfma_f32_16x16x32_bf16 v[50:53], v[154:157], v[164:167], v[50:53]
	v_mfma_f32_16x16x32_bf16 v[50:53], v[160:163], v[182:185], v[50:53]
	v_mfma_f32_16x16x32_bf16 v[38:41], v[146:149], v[186:189], v[38:41]
	v_mfma_f32_16x16x32_bf16 v[38:41], v[150:153], v[190:193], v[38:41]
	v_mfma_f32_16x16x32_bf16 v[34:37], v[154:157], v[186:189], v[34:37]
	v_mfma_f32_16x16x32_bf16 v[34:37], v[160:163], v[190:193], v[34:37]
	v_mfma_f32_16x16x32_bf16 v[22:25], v[146:149], v[194:197], v[22:25]
	v_mfma_f32_16x16x32_bf16 v[22:25], v[150:153], v[198:201], v[22:25]
	v_mfma_f32_16x16x32_bf16 v[18:21], v[154:157], v[194:197], v[18:21]
	v_mfma_f32_16x16x32_bf16 v[18:21], v[160:163], v[198:201], v[18:21]
	v_mfma_f32_16x16x32_bf16 v[6:9], v[146:149], v[212:215], v[6:9]
	v_mfma_f32_16x16x32_bf16 v[6:9], v[150:153], v[216:219], v[6:9]
	v_mfma_f32_16x16x32_bf16 v[2:5], v[154:157], v[212:215], v[2:5]
	v_mfma_f32_16x16x32_bf16 v[2:5], v[160:163], v[216:219], v[2:5]
	s_setprio 0
	s_barrier
	s_add_i32 s55, 0, 0x18000
	s_add_i32 s56, 0, 0x1c000
	v_add_u32_e32 v142, s55, v205
	v_add_u32_e32 v160, s56, v205
	ds_read_b128 v[130:133], v142
	ds_read_b128 v[134:137], v142 offset:1024
	ds_read_b128 v[138:141], v142 offset:2048
	ds_read_b128 v[142:145], v142 offset:3072
	ds_read_b128 v[146:149], v160
	ds_read_b128 v[150:153], v160 offset:1024
	ds_read_b128 v[154:157], v160 offset:2048
	ds_read_b128 v[160:163], v160 offset:3072
	s_add_u32 s48, s48, s74
	s_addc_u32 s49, s49, 0
	s_mov_b32 m0, s9
	v_lshl_add_u64 v[232:233], s[48:49], 0, v[172:173]
	ds_read_b128 v[164:167], v208 offset:32768
	ds_read_b128 v[182:185], v208 offset:33792
	ds_read_b128 v[186:189], v208 offset:34816
	ds_read_b128 v[190:193], v208 offset:35840
	ds_read_b128 v[194:197], v208 offset:36864
	ds_read_b128 v[198:201], v208 offset:37888
	ds_read_b128 v[212:215], v208 offset:38912
	ds_read_b128 v[216:219], v208 offset:39936
	global_load_lds_dwordx4 v[232:233], off
	v_lshl_add_u64 v[232:233], s[48:49], 0, v[168:169]
	s_mov_b32 m0, s10
	s_nop 0
	global_load_lds_dwordx4 v[232:233], off
	s_waitcnt vmcnt(8)
	s_waitcnt lgkmcnt(0)
	s_barrier
	s_setprio 1
	s_waitcnt lgkmcnt(0)
	v_mfma_f32_16x16x32_bf16 v[126:129], v[130:133], v[164:167], v[126:129]
	v_mfma_f32_16x16x32_bf16 v[126:129], v[134:137], v[182:185], v[126:129]
	v_mfma_f32_16x16x32_bf16 v[122:125], v[138:141], v[164:167], v[122:125]
	v_mfma_f32_16x16x32_bf16 v[122:125], v[142:145], v[182:185], v[122:125]
	v_mfma_f32_16x16x32_bf16 v[110:113], v[130:133], v[186:189], v[110:113]
	v_mfma_f32_16x16x32_bf16 v[110:113], v[134:137], v[190:193], v[110:113]
	v_mfma_f32_16x16x32_bf16 v[106:109], v[138:141], v[186:189], v[106:109]
	v_mfma_f32_16x16x32_bf16 v[106:109], v[142:145], v[190:193], v[106:109]
	v_mfma_f32_16x16x32_bf16 v[94:97], v[130:133], v[194:197], v[94:97]
	v_mfma_f32_16x16x32_bf16 v[94:97], v[134:137], v[198:201], v[94:97]
	v_mfma_f32_16x16x32_bf16 v[90:93], v[138:141], v[194:197], v[90:93]
	v_mfma_f32_16x16x32_bf16 v[90:93], v[142:145], v[198:201], v[90:93]
	v_mfma_f32_16x16x32_bf16 v[78:81], v[130:133], v[212:215], v[78:81]
	v_mfma_f32_16x16x32_bf16 v[78:81], v[134:137], v[216:219], v[78:81]
	v_mfma_f32_16x16x32_bf16 v[74:77], v[138:141], v[212:215], v[74:77]
	v_mfma_f32_16x16x32_bf16 v[74:77], v[142:145], v[216:219], v[74:77]
	s_setprio 0
	s_setprio 1
	v_mfma_f32_16x16x32_bf16 v[118:121], v[146:149], v[164:167], v[118:121]
	v_mfma_f32_16x16x32_bf16 v[118:121], v[150:153], v[182:185], v[118:121]
	v_mfma_f32_16x16x32_bf16 v[114:117], v[154:157], v[164:167], v[114:117]
	v_mfma_f32_16x16x32_bf16 v[114:117], v[160:163], v[182:185], v[114:117]
	v_mfma_f32_16x16x32_bf16 v[102:105], v[146:149], v[186:189], v[102:105]
	v_mfma_f32_16x16x32_bf16 v[102:105], v[150:153], v[190:193], v[102:105]
	v_mfma_f32_16x16x32_bf16 v[98:101], v[154:157], v[186:189], v[98:101]
	v_mfma_f32_16x16x32_bf16 v[98:101], v[160:163], v[190:193], v[98:101]
	v_mfma_f32_16x16x32_bf16 v[86:89], v[146:149], v[194:197], v[86:89]
	v_mfma_f32_16x16x32_bf16 v[86:89], v[150:153], v[198:201], v[86:89]
	v_mfma_f32_16x16x32_bf16 v[82:85], v[154:157], v[194:197], v[82:85]
	v_mfma_f32_16x16x32_bf16 v[82:85], v[160:163], v[198:201], v[82:85]
	v_mfma_f32_16x16x32_bf16 v[70:73], v[146:149], v[212:215], v[70:73]
	v_mfma_f32_16x16x32_bf16 v[70:73], v[150:153], v[216:219], v[70:73]
	v_mfma_f32_16x16x32_bf16 v[66:69], v[154:157], v[212:215], v[66:69]
	v_mfma_f32_16x16x32_bf16 v[66:69], v[160:163], v[216:219], v[66:69]
	s_setprio 0
	s_barrier
; #define PG8_STAGE(bufoff, gbase, voff) do { _Pragma("unroll") for (int _i = 0; _i < 2; ++_i) \
;         __builtin_amdgcn_global_load_lds((const unsigned*)((const char*)(gbase) + (voff)[_i]), (PG8_LAS unsigned*)(lds + (bufoff) + ldsw + _i * 8192), 16, 0, 0); } while (0)
; #define PG8_LDA(dst, b, h) do { _Pragma("unroll") for (int m = 0; m < 4; ++m) _Pragma("unroll") for (int k = 0; k < 2; ++k) dst[m][k] = *(const PG8_LAS bf16x8*)(lds + PG8_SA(b, h) + aoff + m * 2048 + k * 1024); } while (0)
; #define PG8_MMA(ai, bj, At, Bt) do { __builtin_amdgcn_s_setprio(1); _Pragma("unroll") for (int m = 0; m < 4; ++m) _Pragma("unroll") for (int n = 0; n < 2; ++n) _Pragma("unroll") for (int k = 0; k < 2; ++k) \
;         acc[ai][bj][m][n] = __builtin_amdgcn_mfma_f32_16x16x32_bf16(Bt[n][k], At[m][k], acc[ai][bj][m][n], 0, 0, 0); __builtin_amdgcn_s_setprio(0); } while (0)
; #define PG8_WAIT_V(n) asm volatile("s_waitcnt vmcnt(" #n ")" ::: "memory")
; #define PG8_WAIT_L(n) asm volatile("s_waitcnt lgkmcnt(" #n ")" ::: "memory")
; #define PG8_BAR __builtin_amdgcn_s_barrier()
; #define PG8_SCHED __builtin_amdgcn_sched_barrier(0)
; template <class Epi, class Sched, bool ALIGN_EPI = false, bool SP2 = false>
; __device__ __forceinline__ void gemm_phase(PG8_LAS unsigned char* lds, const Gemm g, const Sched& S, const Epi& E, const int wave_s) {
;     ...
;             PG8_LDA(At, 1, 1); PG8_STAGE(PG8_SB(1, 0), b3, voffB); PG8_STAGE(PG8_SB(1, 1), b3 + bhstep, voffB); PG8_STAGE(PG8_SA(1, 0), a3, voffA);
;             PG8_WAIT_V(8); PG8_WAIT_L(0); PG8_BAR; PG8_MMA(1, 0, At, B0); PG8_MMA(1, 1, At, B1); PG8_BAR; PG8_SCHED;
	s_add_i32 s48, s55, s5
	v_lshl_add_u64 v[220:221], v[220:221], 0, s[24:25]
	s_mov_b32 m0, s48
	ds_read_b128 v[164:167], v208 offset:49152
	ds_read_b128 v[182:185], v208 offset:50176
	ds_read_b128 v[186:189], v208 offset:51200
	ds_read_b128 v[190:193], v208 offset:52224
	ds_read_b128 v[194:197], v208 offset:53248
	ds_read_b128 v[198:201], v208 offset:54272
	ds_read_b128 v[212:215], v208 offset:55296
	ds_read_b128 v[216:219], v208 offset:56320
	global_load_lds_dwordx4 v[220:221], off
	v_lshl_add_u64 v[220:221], v[222:223], 0, s[24:25]
	s_add_i32 m0, s48, 0x2000
	s_add_i32 s48, s56, s5
	global_load_lds_dwordx4 v[220:221], off
	v_lshl_add_u64 v[220:221], v[224:225], 0, s[24:25]
	s_mov_b32 m0, s48
	s_nop 0
	global_load_lds_dwordx4 v[220:221], off
	v_lshl_add_u64 v[220:221], v[226:227], 0, s[24:25]
	s_add_i32 m0, s48, 0x2000
	s_nop 0
	global_load_lds_dwordx4 v[220:221], off
	v_lshl_add_u64 v[220:221], v[228:229], 0, s[24:25]
	s_mov_b32 m0, s11
	s_nop 0
	global_load_lds_dwordx4 v[220:221], off
	v_lshl_add_u64 v[220:221], v[230:231], 0, s[24:25]
	s_mov_b32 m0, s12
	s_nop 0
	global_load_lds_dwordx4 v[220:221], off
	s_waitcnt vmcnt(8)
	s_waitcnt lgkmcnt(0)
	s_barrier
	s_setprio 1
	s_waitcnt lgkmcnt(0)
	v_mfma_f32_16x16x32_bf16 v[62:65], v[130:133], v[164:167], v[62:65]
	v_mfma_f32_16x16x32_bf16 v[62:65], v[134:137], v[182:185], v[62:65]
	v_mfma_f32_16x16x32_bf16 v[58:61], v[138:141], v[164:167], v[58:61]
	v_mfma_f32_16x16x32_bf16 v[58:61], v[142:145], v[182:185], v[58:61]
	v_mfma_f32_16x16x32_bf16 v[46:49], v[130:133], v[186:189], v[46:49]
	v_mfma_f32_16x16x32_bf16 v[46:49], v[134:137], v[190:193], v[46:49]
	v_mfma_f32_16x16x32_bf16 v[42:45], v[138:141], v[186:189], v[42:45]
	v_mfma_f32_16x16x32_bf16 v[42:45], v[142:145], v[190:193], v[42:45]
	v_mfma_f32_16x16x32_bf16 v[30:33], v[130:133], v[194:197], v[30:33]
	v_mfma_f32_16x16x32_bf16 v[30:33], v[134:137], v[198:201], v[30:33]
	v_mfma_f32_16x16x32_bf16 v[26:29], v[138:141], v[194:197], v[26:29]
	v_mfma_f32_16x16x32_bf16 v[26:29], v[142:145], v[198:201], v[26:29]
	v_mfma_f32_16x16x32_bf16 v[14:17], v[130:133], v[212:215], v[14:17]
	v_mfma_f32_16x16x32_bf16 v[14:17], v[134:137], v[216:219], v[14:17]
	v_mfma_f32_16x16x32_bf16 v[10:13], v[138:141], v[212:215], v[10:13]
	v_mfma_f32_16x16x32_bf16 v[10:13], v[142:145], v[216:219], v[10:13]
	s_setprio 0
	s_setprio 1
	v_mfma_f32_16x16x32_bf16 v[54:57], v[146:149], v[164:167], v[54:57]
	v_mfma_f32_16x16x32_bf16 v[54:57], v[150:153], v[182:185], v[54:57]
	v_mfma_f32_16x16x32_bf16 v[50:53], v[154:157], v[164:167], v[50:53]
	v_mfma_f32_16x16x32_bf16 v[50:53], v[160:163], v[182:185], v[50:53]
	v_mfma_f32_16x16x32_bf16 v[38:41], v[146:149], v[186:189], v[38:41]
	v_mfma_f32_16x16x32_bf16 v[38:41], v[150:153], v[190:193], v[38:41]
	v_mfma_f32_16x16x32_bf16 v[34:37], v[154:157], v[186:189], v[34:37]
	v_mfma_f32_16x16x32_bf16 v[34:37], v[160:163], v[190:193], v[34:37]
	v_mfma_f32_16x16x32_bf16 v[22:25], v[146:149], v[194:197], v[22:25]
	v_mfma_f32_16x16x32_bf16 v[22:25], v[150:153], v[198:201], v[22:25]
	v_mfma_f32_16x16x32_bf16 v[18:21], v[154:157], v[194:197], v[18:21]
	v_mfma_f32_16x16x32_bf16 v[18:21], v[160:163], v[198:201], v[18:21]
	v_mfma_f32_16x16x32_bf16 v[6:9], v[146:149], v[212:215], v[6:9]
	v_mfma_f32_16x16x32_bf16 v[6:9], v[150:153], v[216:219], v[6:9]
	v_mfma_f32_16x16x32_bf16 v[2:5], v[154:157], v[212:215], v[2:5]
	v_mfma_f32_16x16x32_bf16 v[2:5], v[160:163], v[216:219], v[2:5]
	s_setprio 0
	s_barrier
	s_add_u32 s44, s44, 0x100
	s_addc_u32 s45, s45, 0
	s_add_u32 s52, s52, 0x100
	s_addc_u32 s53, s53, 0
	s_cmp_ge_u32 s54, s14
	s_mov_b32 s48, s54
	s_cbranch_scc0 .LBB0_753
	s_and_b64 vcc, exec, s[20:21]
	s_cbranch_vccz .LBB0_756
	s_barrier

; #define PG8_STAGE(bufoff, gbase, voff) do { _Pragma("unroll") for (int _i = 0; _i < 2; ++_i) \
;         __builtin_amdgcn_global_load_lds((const unsigned*)((const char*)(gbase) + (voff)[_i]), (PG8_LAS unsigned*)(lds + (bufoff) + ldsw + _i * 8192), 16, 0, 0); } while (0)
; #define PG8_LDA(dst, b, h) do { _Pragma("unroll") for (int m = 0; m < 4; ++m) _Pragma("unroll") for (int k = 0; k < 2; ++k) dst[m][k] = *(const PG8_LAS bf16x8*)(lds + PG8_SA(b, h) + aoff + m * 2048 + k * 1024); } while (0)
; #define PG8_LDB(dst, b, h) do { _Pragma("unroll") for (int n = 0; n < 2; ++n) _Pragma("unroll") for (int k = 0; k < 2; ++k) dst[n][k] = *(const PG8_LAS bf16x8*)(lds + PG8_SB(b, h) + boff + n * 2048 + k * 1024); } while (0)
; #define PG8_MMA(ai, bj, At, Bt) do { __builtin_amdgcn_s_setprio(1); _Pragma("unroll") for (int m = 0; m < 4; ++m) _Pragma("unroll") for (int n = 0; n < 2; ++n) _Pragma("unroll") for (int k = 0; k < 2; ++k) \
;         acc[ai][bj][m][n] = __builtin_amdgcn_mfma_f32_16x16x32_bf16(Bt[n][k], At[m][k], acc[ai][bj][m][n], 0, 0, 0); __builtin_amdgcn_s_setprio(0); } while (0)
; #define PG8_WAIT_V(n) asm volatile("s_waitcnt vmcnt(" #n ")" ::: "memory")
; #define PG8_WAIT_L(n) asm volatile("s_waitcnt lgkmcnt(" #n ")" ::: "memory")
; template <class Epi, class Sched, bool ALIGN_EPI = false, bool SP2 = false>
; __device__ __forceinline__ void gemm_phase(PG8_LAS unsigned char* lds, const Gemm g, const Sched& S, const Epi& E, const int wave_s) {
;     ...
;             const bool last = (t == nt - 2);
;             const char* a1 = cA + (size_t)(t + 1) * kstep;
;             const char* a2 = last ? nA : cA + (size_t)(t + 2) * kstep; const char* b2 = last ? nB : cB + (size_t)(t + 2) * kstep;
;             const char* a3 = a2 + kstep; const char* b3 = b2 + kstep;
;             if (last && has_next) S.a_ready(nxt);
;             if constexpr (SP2) {
;             PG8_LDB(B0, 0, 0); PG8_LDB(B1, 0, 1); PG8_SCHED; PG8_LDA(At, 0, 0); PG8_STAGE(PG8_SA(1, 1), a1 + hstep, voffA);
;             PG8_WAIT_V(8); PG8_WAIT_L(0); PG8_BAR; PG8_MMA(0, 0, At, B0); PG8_MMA(0, 1, At, B1); PG8_BAR; PG8_SCHED;
;             PG8_LDA(At, 0, 1); PG8_STAGE(PG8_SB(0, 0), b2, voffB); PG8_STAGE(PG8_SB(0, 1), b2 + bhstep, voffB); PG8_STAGE(PG8_SA(0, 0), a2, voffA);
;             PG8_WAIT_V(8); PG8_WAIT_L(0); PG8_BAR; PG8_MMA(1, 0, At, B0); PG8_MMA(1, 1, At, B1); PG8_BAR; PG8_SCHED;
.LBB0_843:
	s_add_u32 s44, s42, 0xfffc0080
	s_addc_u32 s45, s43, -1
	s_add_i32 s52, 0, 0x10000
	s_cmp_eq_u32 s51, 12
	s_cselect_b32 s47, s17, s45
	s_cselect_b32 s46, s29, s44
	v_add_u32_e32 v148, s52, v151
	s_cselect_b32 s45, s23, s50
	s_cselect_b32 s44, s48, s49
	s_add_i32 s54, 0, 0x14000
	ds_read_b128 v[144:147], v148
	ds_read_b128 v[160:163], v148 offset:1024
	ds_read_b128 v[164:167], v148 offset:2048
	s_nop 0
	ds_read_b128 v[168:171], v148 offset:3072
	v_add_u32_e32 v148, s54, v151
	ds_read_b128 v[172:175], v148
	ds_read_b128 v[176:179], v148 offset:1024
	ds_read_b128 v[180:183], v148 offset:2048
	ds_read_b128 v[184:187], v148 offset:3072
	v_lshl_add_u64 v[148:149], s[42:43], 0, v[140:141]
	s_add_i32 m0, s7, 0xc000
	ds_read_b128 v[188:191], v155
	ds_read_b128 v[192:195], v155 offset:1024
	ds_read_b128 v[196:199], v155 offset:2048
	ds_read_b128 v[204:207], v155 offset:3072
	ds_read_b128 v[208:211], v155 offset:4096
	ds_read_b128 v[212:215], v155 offset:5120
	ds_read_b128 v[216:219], v155 offset:6144
	ds_read_b128 v[220:223], v155 offset:7168
	global_load_lds_dwordx4 v[148:149], off
	v_lshl_add_u64 v[148:149], s[42:43], 0, v[142:143]
	s_add_i32 m0, s7, 0xe000
	s_nop 0
	global_load_lds_dwordx4 v[148:149], off
	s_waitcnt vmcnt(8)
	s_waitcnt lgkmcnt(0)
	s_barrier
	s_setprio 1
	s_waitcnt lgkmcnt(0)
	v_mfma_f32_16x16x32_bf16 v[126:129], v[144:147], v[188:191], v[126:129]
	v_mfma_f32_16x16x32_bf16 v[126:129], v[160:163], v[192:195], v[126:129]
	v_mfma_f32_16x16x32_bf16 v[122:125], v[164:167], v[188:191], v[122:125]
	v_mfma_f32_16x16x32_bf16 v[122:125], v[168:171], v[192:195], v[122:125]
	v_mfma_f32_16x16x32_bf16 v[110:113], v[144:147], v[196:199], v[110:113]
	v_mfma_f32_16x16x32_bf16 v[110:113], v[160:163], v[204:207], v[110:113]
	v_mfma_f32_16x16x32_bf16 v[106:109], v[164:167], v[196:199], v[106:109]
	v_mfma_f32_16x16x32_bf16 v[106:109], v[168:171], v[204:207], v[106:109]
	v_mfma_f32_16x16x32_bf16 v[94:97], v[144:147], v[208:211], v[94:97]
	v_mfma_f32_16x16x32_bf16 v[94:97], v[160:163], v[212:215], v[94:97]
	v_mfma_f32_16x16x32_bf16 v[90:93], v[164:167], v[208:211], v[90:93]
	v_mfma_f32_16x16x32_bf16 v[90:93], v[168:171], v[212:215], v[90:93]
	v_mfma_f32_16x16x32_bf16 v[78:81], v[144:147], v[216:219], v[78:81]
	v_mfma_f32_16x16x32_bf16 v[78:81], v[160:163], v[220:223], v[78:81]
	v_mfma_f32_16x16x32_bf16 v[74:77], v[164:167], v[216:219], v[74:77]
	v_mfma_f32_16x16x32_bf16 v[74:77], v[168:171], v[220:223], v[74:77]
	s_setprio 0
	s_setprio 1
	v_mfma_f32_16x16x32_bf16 v[118:121], v[172:175], v[188:191], v[118:121]
	v_mfma_f32_16x16x32_bf16 v[118:121], v[176:179], v[192:195], v[118:121]
	v_mfma_f32_16x16x32_bf16 v[114:117], v[180:183], v[188:191], v[114:117]
	v_mfma_f32_16x16x32_bf16 v[114:117], v[184:187], v[192:195], v[114:117]
	v_mfma_f32_16x16x32_bf16 v[102:105], v[172:175], v[196:199], v[102:105]
	v_mfma_f32_16x16x32_bf16 v[102:105], v[176:179], v[204:207], v[102:105]
	v_mfma_f32_16x16x32_bf16 v[98:101], v[180:183], v[196:199], v[98:101]
	v_mfma_f32_16x16x32_bf16 v[98:101], v[184:187], v[204:207], v[98:101]
	v_mfma_f32_16x16x32_bf16 v[86:89], v[172:175], v[208:211], v[86:89]
	v_mfma_f32_16x16x32_bf16 v[86:89], v[176:179], v[212:215], v[86:89]
	v_mfma_f32_16x16x32_bf16 v[82:85], v[180:183], v[208:211], v[82:85]
	v_mfma_f32_16x16x32_bf16 v[82:85], v[184:187], v[212:215], v[82:85]
	v_mfma_f32_16x16x32_bf16 v[70:73], v[172:175], v[216:219], v[70:73]
	v_mfma_f32_16x16x32_bf16 v[70:73], v[176:179], v[220:223], v[70:73]
	v_mfma_f32_16x16x32_bf16 v[66:69], v[180:183], v[216:219], v[66:69]
	v_mfma_f32_16x16x32_bf16 v[66:69], v[184:187], v[220:223], v[66:69]
	s_setprio 0
	s_barrier
	s_add_i32 s52, s52, s6
	v_lshl_add_u64 v[148:149], s[44:45], 0, v[134:135]
	s_mov_b32 m0, s52
	ds_read_b128 v[188:191], v155 offset:16384
	ds_read_b128 v[192:195], v155 offset:17408
	ds_read_b128 v[196:199], v155 offset:18432
	ds_read_b128 v[204:207], v155 offset:19456
	ds_read_b128 v[208:211], v155 offset:20480
	ds_read_b128 v[212:215], v155 offset:21504
	ds_read_b128 v[216:219], v155 offset:22528
	ds_read_b128 v[220:223], v155 offset:23552
	global_load_lds_dwordx4 v[148:149], off
	s_add_i32 m0, s52, 0x2000
	s_add_u32 s52, s44, 0x10000
	v_lshl_add_u64 v[200:201], s[44:45], 0, v[138:139]
	s_addc_u32 s53, s45, 0
	s_add_i32 s54, s54, s6
	global_load_lds_dwordx4 v[200:201], off
	v_lshl_add_u64 v[224:225], s[52:53], 0, v[134:135]
	s_mov_b32 m0, s54
	v_lshl_add_u64 v[226:227], s[46:47], 0, v[136:137]
	global_load_lds_dwordx4 v[224:225], off
	v_lshl_add_u64 v[224:225], s[52:53], 0, v[138:139]
	s_add_i32 m0, s54, 0x2000
	s_nop 0
	global_load_lds_dwordx4 v[224:225], off
	v_lshl_add_u64 v[224:225], s[46:47], 0, v[132:133]
	s_mov_b32 m0, s7
	s_nop 0
	global_load_lds_dwordx4 v[224:225], off
	s_mov_b32 m0, s8
	s_nop 0
	global_load_lds_dwordx4 v[226:227], off
	s_waitcnt vmcnt(8)
	s_waitcnt lgkmcnt(0)
	s_barrier
; #define PG8_STAGE(bufoff, gbase, voff) do { _Pragma("unroll") for (int _i = 0; _i < 2; ++_i) \
;         __builtin_amdgcn_global_load_lds((const unsigned*)((const char*)(gbase) + (voff)[_i]), (PG8_LAS unsigned*)(lds + (bufoff) + ldsw + _i * 8192), 16, 0, 0); } while (0)
; #define PG8_LDA(dst, b, h) do { _Pragma("unroll") for (int m = 0; m < 4; ++m) _Pragma("unroll") for (int k = 0; k < 2; ++k) dst[m][k] = *(const PG8_LAS bf16x8*)(lds + PG8_SA(b, h) + aoff + m * 2048 + k * 1024); } while (0)
; #define PG8_LDB(dst, b, h) do { _Pragma("unroll") for (int n = 0; n < 2; ++n) _Pragma("unroll") for (int k = 0; k < 2; ++k) dst[n][k] = *(const PG8_LAS bf16x8*)(lds + PG8_SB(b, h) + boff + n * 2048 + k * 1024); } while (0)
; #define PG8_MMA(ai, bj, At, Bt) do { __builtin_amdgcn_s_setprio(1); _Pragma("unroll") for (int m = 0; m < 4; ++m) _Pragma("unroll") for (int n = 0; n < 2; ++n) _Pragma("unroll") for (int k = 0; k < 2; ++k) \
;         acc[ai][bj][m][n] = __builtin_amdgcn_mfma_f32_16x16x32_bf16(Bt[n][k], At[m][k], acc[ai][bj][m][n], 0, 0, 0); __builtin_amdgcn_s_setprio(0); } while (0)
; #define PG8_WAIT_V(n) asm volatile("s_waitcnt vmcnt(" #n ")" ::: "memory")
; #define PG8_WAIT_L(n) asm volatile("s_waitcnt lgkmcnt(" #n ")" ::: "memory")
; #define PG8_BAR __builtin_amdgcn_s_barrier()
; #define PG8_SCHED __builtin_amdgcn_sched_barrier(0)
; template <class Epi, class Sched, bool ALIGN_EPI = false, bool SP2 = false>
; __device__ __forceinline__ void gemm_phase(PG8_LAS unsigned char* lds, const Gemm g, const Sched& S, const Epi& E, const int wave_s) {
;     ...
;             PG8_WAIT_V(8); PG8_WAIT_L(0); PG8_BAR; PG8_MMA(1, 0, At, B0); PG8_MMA(1, 1, At, B1); PG8_BAR; PG8_SCHED;
;             PG8_LDB(B0, 1, 0); PG8_LDB(B1, 1, 1); PG8_SCHED; PG8_LDA(At, 1, 0); PG8_STAGE(PG8_SA(0, 1), a2 + hstep, voffA);
;             PG8_WAIT_V(8); PG8_WAIT_L(0); PG8_BAR; PG8_MMA(0, 0, At, B0); PG8_MMA(0, 1, At, B1); PG8_BAR; PG8_SCHED;
	s_setprio 1
	s_waitcnt lgkmcnt(0)
	v_mfma_f32_16x16x32_bf16 v[62:65], v[144:147], v[188:191], v[62:65]
	v_mfma_f32_16x16x32_bf16 v[62:65], v[160:163], v[192:195], v[62:65]
	v_mfma_f32_16x16x32_bf16 v[58:61], v[164:167], v[188:191], v[58:61]
	v_mfma_f32_16x16x32_bf16 v[58:61], v[168:171], v[192:195], v[58:61]
	v_mfma_f32_16x16x32_bf16 v[46:49], v[144:147], v[196:199], v[46:49]
	v_mfma_f32_16x16x32_bf16 v[46:49], v[160:163], v[204:207], v[46:49]
	v_mfma_f32_16x16x32_bf16 v[42:45], v[164:167], v[196:199], v[42:45]
	v_mfma_f32_16x16x32_bf16 v[42:45], v[168:171], v[204:207], v[42:45]
	v_mfma_f32_16x16x32_bf16 v[30:33], v[144:147], v[208:211], v[30:33]
	v_mfma_f32_16x16x32_bf16 v[30:33], v[160:163], v[212:215], v[30:33]
	v_mfma_f32_16x16x32_bf16 v[26:29], v[164:167], v[208:211], v[26:29]
	v_mfma_f32_16x16x32_bf16 v[26:29], v[168:171], v[212:215], v[26:29]
	v_mfma_f32_16x16x32_bf16 v[14:17], v[144:147], v[216:219], v[14:17]
	v_mfma_f32_16x16x32_bf16 v[14:17], v[160:163], v[220:223], v[14:17]
	v_mfma_f32_16x16x32_bf16 v[10:13], v[164:167], v[216:219], v[10:13]
	v_mfma_f32_16x16x32_bf16 v[10:13], v[168:171], v[220:223], v[10:13]
	s_setprio 0
	s_setprio 1
	v_mfma_f32_16x16x32_bf16 v[54:57], v[172:175], v[188:191], v[54:57]
	v_mfma_f32_16x16x32_bf16 v[54:57], v[176:179], v[192:195], v[54:57]
	v_mfma_f32_16x16x32_bf16 v[50:53], v[180:183], v[188:191], v[50:53]
	v_mfma_f32_16x16x32_bf16 v[50:53], v[184:187], v[192:195], v[50:53]
	v_mfma_f32_16x16x32_bf16 v[38:41], v[172:175], v[196:199], v[38:41]
	v_mfma_f32_16x16x32_bf16 v[38:41], v[176:179], v[204:207], v[38:41]
	v_mfma_f32_16x16x32_bf16 v[34:37], v[180:183], v[196:199], v[34:37]
	v_mfma_f32_16x16x32_bf16 v[34:37], v[184:187], v[204:207], v[34:37]
	v_mfma_f32_16x16x32_bf16 v[22:25], v[172:175], v[208:211], v[22:25]
	v_mfma_f32_16x16x32_bf16 v[22:25], v[176:179], v[212:215], v[22:25]
	v_mfma_f32_16x16x32_bf16 v[18:21], v[180:183], v[208:211], v[18:21]
	v_mfma_f32_16x16x32_bf16 v[18:21], v[184:187], v[212:215], v[18:21]
	v_mfma_f32_16x16x32_bf16 v[6:9], v[172:175], v[216:219], v[6:9]
	v_mfma_f32_16x16x32_bf16 v[6:9], v[176:179], v[220:223], v[6:9]
	v_mfma_f32_16x16x32_bf16 v[2:5], v[180:183], v[216:219], v[2:5]
	v_mfma_f32_16x16x32_bf16 v[2:5], v[184:187], v[220:223], v[2:5]
	s_setprio 0
	s_barrier
	s_add_i32 s52, 0, 0x18000
	v_add_u32_e32 v159, s52, v151
	s_add_i32 s53, 0, 0x1c000
	ds_read_b128 v[144:147], v159
	ds_read_b128 v[160:163], v159 offset:1024
	ds_read_b128 v[164:167], v159 offset:2048
	ds_read_b128 v[168:171], v159 offset:3072
	v_add_u32_e32 v159, s53, v151
	ds_read_b128 v[172:175], v159
	ds_read_b128 v[176:179], v159 offset:1024
	ds_read_b128 v[180:183], v159 offset:2048
	ds_read_b128 v[184:187], v159 offset:3072
	s_add_u32 s46, s46, 0x40000
	s_addc_u32 s47, s47, 0
	s_mov_b32 m0, s9
	v_lshl_add_u64 v[228:229], s[46:47], 0, v[132:133]
	ds_read_b128 v[188:191], v155 offset:32768
	ds_read_b128 v[192:195], v155 offset:33792
	ds_read_b128 v[196:199], v155 offset:34816
	ds_read_b128 v[204:207], v155 offset:35840
	ds_read_b128 v[208:211], v155 offset:36864
	ds_read_b128 v[212:215], v155 offset:37888
	ds_read_b128 v[216:219], v155 offset:38912
	ds_read_b128 v[220:223], v155 offset:39936
	global_load_lds_dwordx4 v[228:229], off
	v_lshl_add_u64 v[228:229], s[46:47], 0, v[136:137]
	s_mov_b32 m0, s10
	s_nop 0
	global_load_lds_dwordx4 v[228:229], off
	s_waitcnt vmcnt(8)
	s_waitcnt lgkmcnt(0)
	s_barrier
	s_setprio 1
	s_waitcnt lgkmcnt(0)
	v_mfma_f32_16x16x32_bf16 v[126:129], v[144:147], v[188:191], v[126:129]
	v_mfma_f32_16x16x32_bf16 v[126:129], v[160:163], v[192:195], v[126:129]
	v_mfma_f32_16x16x32_bf16 v[122:125], v[164:167], v[188:191], v[122:125]
	v_mfma_f32_16x16x32_bf16 v[122:125], v[168:171], v[192:195], v[122:125]
	v_mfma_f32_16x16x32_bf16 v[110:113], v[144:147], v[196:199], v[110:113]
	v_mfma_f32_16x16x32_bf16 v[110:113], v[160:163], v[204:207], v[110:113]
	v_mfma_f32_16x16x32_bf16 v[106:109], v[164:167], v[196:199], v[106:109]
	v_mfma_f32_16x16x32_bf16 v[106:109], v[168:171], v[204:207], v[106:109]
	v_mfma_f32_16x16x32_bf16 v[94:97], v[144:147], v[208:211], v[94:97]
	v_mfma_f32_16x16x32_bf16 v[94:97], v[160:163], v[212:215], v[94:97]
	v_mfma_f32_16x16x32_bf16 v[90:93], v[164:167], v[208:211], v[90:93]
	v_mfma_f32_16x16x32_bf16 v[90:93], v[168:171], v[212:215], v[90:93]
	v_mfma_f32_16x16x32_bf16 v[78:81], v[144:147], v[216:219], v[78:81]
	v_mfma_f32_16x16x32_bf16 v[78:81], v[160:163], v[220:223], v[78:81]
	v_mfma_f32_16x16x32_bf16 v[74:77], v[164:167], v[216:219], v[74:77]
	v_mfma_f32_16x16x32_bf16 v[74:77], v[168:171], v[220:223], v[74:77]
	s_setprio 0
	s_setprio 1
	v_mfma_f32_16x16x32_bf16 v[118:121], v[172:175], v[188:191], v[118:121]
	v_mfma_f32_16x16x32_bf16 v[118:121], v[176:179], v[192:195], v[118:121]
	v_mfma_f32_16x16x32_bf16 v[114:117], v[180:183], v[188:191], v[114:117]
	v_mfma_f32_16x16x32_bf16 v[114:117], v[184:187], v[192:195], v[114:117]
	v_mfma_f32_16x16x32_bf16 v[102:105], v[172:175], v[196:199], v[102:105]
	v_mfma_f32_16x16x32_bf16 v[102:105], v[176:179], v[204:207], v[102:105]
	v_mfma_f32_16x16x32_bf16 v[98:101], v[180:183], v[196:199], v[98:101]
	v_mfma_f32_16x16x32_bf16 v[98:101], v[184:187], v[204:207], v[98:101]
	v_mfma_f32_16x16x32_bf16 v[86:89], v[172:175], v[208:211], v[86:89]
	v_mfma_f32_16x16x32_bf16 v[86:89], v[176:179], v[212:215], v[86:89]
	v_mfma_f32_16x16x32_bf16 v[82:85], v[180:183], v[208:211], v[82:85]
	v_mfma_f32_16x16x32_bf16 v[82:85], v[184:187], v[212:215], v[82:85]
	v_mfma_f32_16x16x32_bf16 v[70:73], v[172:175], v[216:219], v[70:73]
	v_mfma_f32_16x16x32_bf16 v[70:73], v[176:179], v[220:223], v[70:73]
	v_mfma_f32_16x16x32_bf16 v[66:69], v[180:183], v[216:219], v[66:69]
	v_mfma_f32_16x16x32_bf16 v[66:69], v[184:187], v[220:223], v[66:69]
	s_setprio 0
	s_barrier
; #define PG8_STAGE(bufoff, gbase, voff) do { _Pragma("unroll") for (int _i = 0; _i < 2; ++_i) \
;         __builtin_amdgcn_global_load_lds((const unsigned*)((const char*)(gbase) + (voff)[_i]), (PG8_LAS unsigned*)(lds + (bufoff) + ldsw + _i * 8192), 16, 0, 0); } while (0)
; #define PG8_LDA(dst, b, h) do { _Pragma("unroll") for (int m = 0; m < 4; ++m) _Pragma("unroll") for (int k = 0; k < 2; ++k) dst[m][k] = *(const PG8_LAS bf16x8*)(lds + PG8_SA(b, h) + aoff + m * 2048 + k * 1024); } while (0)
; #define PG8_MMA(ai, bj, At, Bt) do { __builtin_amdgcn_s_setprio(1); _Pragma("unroll") for (int m = 0; m < 4; ++m) _Pragma("unroll") for (int n = 0; n < 2; ++n) _Pragma("unroll") for (int k = 0; k < 2; ++k) \
;         acc[ai][bj][m][n] = __builtin_amdgcn_mfma_f32_16x16x32_bf16(Bt[n][k], At[m][k], acc[ai][bj][m][n], 0, 0, 0); __builtin_amdgcn_s_setprio(0); } while (0)
; #define PG8_WAIT_V(n) asm volatile("s_waitcnt vmcnt(" #n ")" ::: "memory")
; #define PG8_WAIT_L(n) asm volatile("s_waitcnt lgkmcnt(" #n ")" ::: "memory")
; #define PG8_BAR __builtin_amdgcn_s_barrier()
; #define PG8_SCHED __builtin_amdgcn_sched_barrier(0)
; template <class Epi, class Sched, bool ALIGN_EPI = false, bool SP2 = false>
; __device__ __forceinline__ void gemm_phase(PG8_LAS unsigned char* lds, const Gemm g, const Sched& S, const Epi& E, const int wave_s) {
;     ...
;             PG8_LDA(At, 1, 1); PG8_STAGE(PG8_SB(1, 0), b3, voffB); PG8_STAGE(PG8_SB(1, 1), b3 + bhstep, voffB); PG8_STAGE(PG8_SA(1, 0), a3, voffA);
;             PG8_WAIT_V(8); PG8_WAIT_L(0); PG8_BAR; PG8_MMA(1, 0, At, B0); PG8_MMA(1, 1, At, B1); PG8_BAR; PG8_SCHED;
	s_add_i32 s46, s52, s6
	v_lshl_add_u64 v[148:149], v[148:149], 0, s[24:25]
	s_mov_b32 m0, s46
	ds_read_b128 v[188:191], v155 offset:49152
	ds_read_b128 v[192:195], v155 offset:50176
	ds_read_b128 v[196:199], v155 offset:51200
	ds_read_b128 v[204:207], v155 offset:52224
	ds_read_b128 v[208:211], v155 offset:53248
	ds_read_b128 v[212:215], v155 offset:54272
	ds_read_b128 v[216:219], v155 offset:55296
	ds_read_b128 v[220:223], v155 offset:56320
	global_load_lds_dwordx4 v[148:149], off
	s_add_i32 m0, s46, 0x2000
	s_add_u32 s44, s44, 0x10080
	v_lshl_add_u64 v[148:149], v[200:201], 0, s[24:25]
	s_addc_u32 s45, s45, 0
	s_add_i32 s46, s53, s6
	global_load_lds_dwordx4 v[148:149], off
	v_lshl_add_u64 v[148:149], s[44:45], 0, v[134:135]
	s_mov_b32 m0, s46
	s_nop 0
	global_load_lds_dwordx4 v[148:149], off
	v_lshl_add_u64 v[148:149], s[44:45], 0, v[138:139]
	s_add_i32 m0, s46, 0x2000
	s_nop 0
	global_load_lds_dwordx4 v[148:149], off
	v_lshl_add_u64 v[148:149], v[224:225], 0, s[24:25]
	s_mov_b32 m0, s11
	s_nop 0
	global_load_lds_dwordx4 v[148:149], off
	v_lshl_add_u64 v[148:149], v[226:227], 0, s[24:25]
	s_mov_b32 m0, s12
	s_nop 0
	global_load_lds_dwordx4 v[148:149], off
	s_waitcnt vmcnt(8)
	s_waitcnt lgkmcnt(0)
	s_barrier
	s_setprio 1
	s_waitcnt lgkmcnt(0)
	v_mfma_f32_16x16x32_bf16 v[62:65], v[144:147], v[188:191], v[62:65]
	v_mfma_f32_16x16x32_bf16 v[62:65], v[160:163], v[192:195], v[62:65]
	v_mfma_f32_16x16x32_bf16 v[58:61], v[164:167], v[188:191], v[58:61]
	v_mfma_f32_16x16x32_bf16 v[58:61], v[168:171], v[192:195], v[58:61]
	v_mfma_f32_16x16x32_bf16 v[46:49], v[144:147], v[196:199], v[46:49]
	v_mfma_f32_16x16x32_bf16 v[46:49], v[160:163], v[204:207], v[46:49]
	v_mfma_f32_16x16x32_bf16 v[42:45], v[164:167], v[196:199], v[42:45]
	v_mfma_f32_16x16x32_bf16 v[42:45], v[168:171], v[204:207], v[42:45]
	v_mfma_f32_16x16x32_bf16 v[30:33], v[144:147], v[208:211], v[30:33]
	v_mfma_f32_16x16x32_bf16 v[30:33], v[160:163], v[212:215], v[30:33]
	v_mfma_f32_16x16x32_bf16 v[26:29], v[164:167], v[208:211], v[26:29]
	v_mfma_f32_16x16x32_bf16 v[26:29], v[168:171], v[212:215], v[26:29]
	v_mfma_f32_16x16x32_bf16 v[14:17], v[144:147], v[216:219], v[14:17]
	v_mfma_f32_16x16x32_bf16 v[14:17], v[160:163], v[220:223], v[14:17]
	v_mfma_f32_16x16x32_bf16 v[10:13], v[164:167], v[216:219], v[10:13]
	v_mfma_f32_16x16x32_bf16 v[10:13], v[168:171], v[220:223], v[10:13]
	s_setprio 0
	s_setprio 1
	v_mfma_f32_16x16x32_bf16 v[54:57], v[172:175], v[188:191], v[54:57]
	v_mfma_f32_16x16x32_bf16 v[54:57], v[176:179], v[192:195], v[54:57]
	v_mfma_f32_16x16x32_bf16 v[50:53], v[180:183], v[188:191], v[50:53]
	v_mfma_f32_16x16x32_bf16 v[50:53], v[184:187], v[192:195], v[50:53]
	v_mfma_f32_16x16x32_bf16 v[38:41], v[172:175], v[196:199], v[38:41]
	v_mfma_f32_16x16x32_bf16 v[38:41], v[176:179], v[204:207], v[38:41]
	v_mfma_f32_16x16x32_bf16 v[34:37], v[180:183], v[196:199], v[34:37]
	v_mfma_f32_16x16x32_bf16 v[34:37], v[184:187], v[204:207], v[34:37]
	v_mfma_f32_16x16x32_bf16 v[22:25], v[172:175], v[208:211], v[22:25]
	v_mfma_f32_16x16x32_bf16 v[22:25], v[176:179], v[212:215], v[22:25]
	v_mfma_f32_16x16x32_bf16 v[18:21], v[180:183], v[208:211], v[18:21]
	v_mfma_f32_16x16x32_bf16 v[18:21], v[184:187], v[212:215], v[18:21]
	v_mfma_f32_16x16x32_bf16 v[6:9], v[172:175], v[216:219], v[6:9]
	v_mfma_f32_16x16x32_bf16 v[6:9], v[176:179], v[220:223], v[6:9]
	v_mfma_f32_16x16x32_bf16 v[2:5], v[180:183], v[216:219], v[2:5]
	v_mfma_f32_16x16x32_bf16 v[2:5], v[184:187], v[220:223], v[2:5]
	s_setprio 0
	s_barrier
	s_add_i32 s51, s51, 2
	s_add_u32 s42, s42, 0x100
	s_addc_u32 s43, s43, 0
	s_add_u32 s49, s49, 0x100
	s_addc_u32 s50, s50, 0
	s_cmp_gt_u32 s51, 13
	s_cbranch_scc0 .LBB0_843
	s_and_b64 vcc, exec, s[20:21]
	s_cbranch_vccz .LBB0_846
	s_barrier

; #define PG8_STAGE(bufoff, gbase, voff) do { _Pragma("unroll") for (int _i = 0; _i < 2; ++_i) \
;         __builtin_amdgcn_global_load_lds((const unsigned*)((const char*)(gbase) + (voff)[_i]), (PG8_LAS unsigned*)(lds + (bufoff) + ldsw + _i * 8192), 16, 0, 0); } while (0)
; #define PG8_LDA(dst, b, h) do { _Pragma("unroll") for (int m = 0; m < 4; ++m) _Pragma("unroll") for (int k = 0; k < 2; ++k) dst[m][k] = *(const PG8_LAS bf16x8*)(lds + PG8_SA(b, h) + aoff + m * 2048 + k * 1024); } while (0)
; #define PG8_LDB(dst, b, h) do { _Pragma("unroll") for (int n = 0; n < 2; ++n) _Pragma("unroll") for (int k = 0; k < 2; ++k) dst[n][k] = *(const PG8_LAS bf16x8*)(lds + PG8_SB(b, h) + boff + n * 2048 + k * 1024); } while (0)
; #define PG8_MMA(ai, bj, At, Bt) do { __builtin_amdgcn_s_setprio(1); _Pragma("unroll") for (int m = 0; m < 4; ++m) _Pragma("unroll") for (int n = 0; n < 2; ++n) _Pragma("unroll") for (int k = 0; k < 2; ++k) \
;         acc[ai][bj][m][n] = __builtin_amdgcn_mfma_f32_16x16x32_bf16(Bt[n][k], At[m][k], acc[ai][bj][m][n], 0, 0, 0); __builtin_amdgcn_s_setprio(0); } while (0)
; #define PG8_WAIT_V(n) asm volatile("s_waitcnt vmcnt(" #n ")" ::: "memory")
; #define PG8_WAIT_L(n) asm volatile("s_waitcnt lgkmcnt(" #n ")" ::: "memory")
; template <class Epi, class Sched, bool ALIGN_EPI = false, bool SP2 = false>
; __device__ __forceinline__ void gemm_phase(PG8_LAS unsigned char* lds, const Gemm g, const Sched& S, const Epi& E, const int wave_s) {
;     ...
;             const bool last = (t == nt - 2);
;             const char* a1 = cA + (size_t)(t + 1) * kstep;
;             const char* a2 = last ? nA : cA + (size_t)(t + 2) * kstep; const char* b2 = last ? nB : cB + (size_t)(t + 2) * kstep;
;             const char* a3 = a2 + kstep; const char* b3 = b2 + kstep;
;             if (last && has_next) S.a_ready(nxt);
;             if constexpr (SP2) {
;             PG8_LDB(B0, 0, 0); PG8_LDB(B1, 0, 1); PG8_SCHED; PG8_LDA(At, 0, 0); PG8_STAGE(PG8_SA(1, 1), a1 + hstep, voffA);
;             PG8_WAIT_V(8); PG8_WAIT_L(0); PG8_BAR; PG8_MMA(0, 0, At, B0); PG8_MMA(0, 1, At, B1); PG8_BAR; PG8_SCHED;
;             PG8_LDA(At, 0, 1); PG8_STAGE(PG8_SB(0, 0), b2, voffB); PG8_STAGE(PG8_SB(0, 1), b2 + bhstep, voffB); PG8_STAGE(PG8_SA(0, 0), a2, voffA);
;             PG8_WAIT_V(8); PG8_WAIT_L(0); PG8_BAR; PG8_MMA(1, 0, At, B0); PG8_MMA(1, 1, At, B1); PG8_BAR; PG8_SCHED;
.LBB0_923:
	s_add_u32 s46, s42, 0xfff00080
	s_addc_u32 s47, s43, -1
	s_add_i32 s51, 0, 0x10000
	s_cmp_eq_u32 s50, 60
	s_cselect_b32 s49, s15, s47
	s_cselect_b32 s48, s16, s46
	s_cselect_b32 s47, s17, s45
	s_cselect_b32 s46, s23, s29
	s_add_i32 s54, 0, 0x14000
	v_add_u32_e32 v142, s51, v205
	v_add_u32_e32 v160, s54, v205
	ds_read_b128 v[130:133], v142
	ds_read_b128 v[134:137], v142 offset:1024
	ds_read_b128 v[138:141], v142 offset:2048
	ds_read_b128 v[142:145], v142 offset:3072
	ds_read_b128 v[146:149], v160
	ds_read_b128 v[150:153], v160 offset:1024
	ds_read_b128 v[154:157], v160 offset:2048
	ds_read_b128 v[160:163], v160 offset:3072
	v_lshl_add_u64 v[220:221], s[42:43], 0, v[178:179]
	s_add_i32 m0, s5, 0xc000
	ds_read_b128 v[164:167], v208
	ds_read_b128 v[182:185], v208 offset:1024
	ds_read_b128 v[186:189], v208 offset:2048
	ds_read_b128 v[190:193], v208 offset:3072
	ds_read_b128 v[194:197], v208 offset:4096
	ds_read_b128 v[198:201], v208 offset:5120
	ds_read_b128 v[212:215], v208 offset:6144
	ds_read_b128 v[216:219], v208 offset:7168
	global_load_lds_dwordx4 v[220:221], off
	v_lshl_add_u64 v[220:221], s[42:43], 0, v[180:181]
	s_add_i32 m0, s5, 0xe000
	s_nop 0
	global_load_lds_dwordx4 v[220:221], off
	s_waitcnt vmcnt(8)
	s_waitcnt lgkmcnt(0)
	s_barrier
	s_setprio 1
	s_waitcnt lgkmcnt(0)
	v_mfma_f32_16x16x32_bf16 v[126:129], v[130:133], v[164:167], v[126:129]
	v_mfma_f32_16x16x32_bf16 v[126:129], v[134:137], v[182:185], v[126:129]
	v_mfma_f32_16x16x32_bf16 v[122:125], v[138:141], v[164:167], v[122:125]
	v_mfma_f32_16x16x32_bf16 v[122:125], v[142:145], v[182:185], v[122:125]
	v_mfma_f32_16x16x32_bf16 v[110:113], v[130:133], v[186:189], v[110:113]
	v_mfma_f32_16x16x32_bf16 v[110:113], v[134:137], v[190:193], v[110:113]
	v_mfma_f32_16x16x32_bf16 v[106:109], v[138:141], v[186:189], v[106:109]
	v_mfma_f32_16x16x32_bf16 v[106:109], v[142:145], v[190:193], v[106:109]
	v_mfma_f32_16x16x32_bf16 v[94:97], v[130:133], v[194:197], v[94:97]
	v_mfma_f32_16x16x32_bf16 v[94:97], v[134:137], v[198:201], v[94:97]
	v_mfma_f32_16x16x32_bf16 v[90:93], v[138:141], v[194:197], v[90:93]
	v_mfma_f32_16x16x32_bf16 v[90:93], v[142:145], v[198:201], v[90:93]
	v_mfma_f32_16x16x32_bf16 v[78:81], v[130:133], v[212:215], v[78:81]
	v_mfma_f32_16x16x32_bf16 v[78:81], v[134:137], v[216:219], v[78:81]
	v_mfma_f32_16x16x32_bf16 v[74:77], v[138:141], v[212:215], v[74:77]
	v_mfma_f32_16x16x32_bf16 v[74:77], v[142:145], v[216:219], v[74:77]
	s_setprio 0
	s_setprio 1
	v_mfma_f32_16x16x32_bf16 v[118:121], v[146:149], v[164:167], v[118:121]
	v_mfma_f32_16x16x32_bf16 v[118:121], v[150:153], v[182:185], v[118:121]
	v_mfma_f32_16x16x32_bf16 v[114:117], v[154:157], v[164:167], v[114:117]
	v_mfma_f32_16x16x32_bf16 v[114:117], v[160:163], v[182:185], v[114:117]
	v_mfma_f32_16x16x32_bf16 v[102:105], v[146:149], v[186:189], v[102:105]
	v_mfma_f32_16x16x32_bf16 v[102:105], v[150:153], v[190:193], v[102:105]
	v_mfma_f32_16x16x32_bf16 v[98:101], v[154:157], v[186:189], v[98:101]
	v_mfma_f32_16x16x32_bf16 v[98:101], v[160:163], v[190:193], v[98:101]
	v_mfma_f32_16x16x32_bf16 v[86:89], v[146:149], v[194:197], v[86:89]
	v_mfma_f32_16x16x32_bf16 v[86:89], v[150:153], v[198:201], v[86:89]
	v_mfma_f32_16x16x32_bf16 v[82:85], v[154:157], v[194:197], v[82:85]
	v_mfma_f32_16x16x32_bf16 v[82:85], v[160:163], v[198:201], v[82:85]
	v_mfma_f32_16x16x32_bf16 v[70:73], v[146:149], v[212:215], v[70:73]
	v_mfma_f32_16x16x32_bf16 v[70:73], v[150:153], v[216:219], v[70:73]
	v_mfma_f32_16x16x32_bf16 v[66:69], v[154:157], v[212:215], v[66:69]
	v_mfma_f32_16x16x32_bf16 v[66:69], v[160:163], v[216:219], v[66:69]
	s_setprio 0
	s_barrier
	s_add_i32 s51, s51, s4
	v_lshl_add_u64 v[220:221], s[46:47], 0, v[170:171]
	s_mov_b32 m0, s51
	ds_read_b128 v[164:167], v208 offset:16384
	ds_read_b128 v[182:185], v208 offset:17408
	ds_read_b128 v[186:189], v208 offset:18432
	ds_read_b128 v[190:193], v208 offset:19456
	ds_read_b128 v[194:197], v208 offset:20480
	ds_read_b128 v[198:201], v208 offset:21504
	ds_read_b128 v[212:215], v208 offset:22528
	ds_read_b128 v[216:219], v208 offset:23552
	global_load_lds_dwordx4 v[220:221], off
	s_add_i32 m0, s51, 0x2000
	s_add_u32 s52, s46, 0x40000
	v_lshl_add_u64 v[222:223], s[46:47], 0, v[158:159]
	s_addc_u32 s53, s47, 0
	s_add_i32 s51, s54, s4
	global_load_lds_dwordx4 v[222:223], off
	v_lshl_add_u64 v[224:225], s[52:53], 0, v[170:171]
	s_mov_b32 m0, s51
	v_lshl_add_u64 v[226:227], s[48:49], 0, v[168:169]
	global_load_lds_dwordx4 v[224:225], off
	v_lshl_add_u64 v[224:225], s[52:53], 0, v[158:159]
	s_add_i32 m0, s51, 0x2000
	s_nop 0
	global_load_lds_dwordx4 v[224:225], off
	v_lshl_add_u64 v[224:225], s[48:49], 0, v[172:173]
	s_mov_b32 m0, s5
	s_nop 0
	global_load_lds_dwordx4 v[224:225], off
	s_mov_b32 m0, s6
	s_nop 0
	global_load_lds_dwordx4 v[226:227], off
	s_waitcnt vmcnt(8)
	s_waitcnt lgkmcnt(0)
	s_barrier
; #define PG8_STAGE(bufoff, gbase, voff) do { _Pragma("unroll") for (int _i = 0; _i < 2; ++_i) \
;         __builtin_amdgcn_global_load_lds((const unsigned*)((const char*)(gbase) + (voff)[_i]), (PG8_LAS unsigned*)(lds + (bufoff) + ldsw + _i * 8192), 16, 0, 0); } while (0)
; #define PG8_LDA(dst, b, h) do { _Pragma("unroll") for (int m = 0; m < 4; ++m) _Pragma("unroll") for (int k = 0; k < 2; ++k) dst[m][k] = *(const PG8_LAS bf16x8*)(lds + PG8_SA(b, h) + aoff + m * 2048 + k * 1024); } while (0)
; #define PG8_LDB(dst, b, h) do { _Pragma("unroll") for (int n = 0; n < 2; ++n) _Pragma("unroll") for (int k = 0; k < 2; ++k) dst[n][k] = *(const PG8_LAS bf16x8*)(lds + PG8_SB(b, h) + boff + n * 2048 + k * 1024); } while (0)
; #define PG8_MMA(ai, bj, At, Bt) do { __builtin_amdgcn_s_setprio(1); _Pragma("unroll") for (int m = 0; m < 4; ++m) _Pragma("unroll") for (int n = 0; n < 2; ++n) _Pragma("unroll") for (int k = 0; k < 2; ++k) \
;         acc[ai][bj][m][n] = __builtin_amdgcn_mfma_f32_16x16x32_bf16(Bt[n][k], At[m][k], acc[ai][bj][m][n], 0, 0, 0); __builtin_amdgcn_s_setprio(0); } while (0)
; #define PG8_WAIT_V(n) asm volatile("s_waitcnt vmcnt(" #n ")" ::: "memory")
; #define PG8_WAIT_L(n) asm volatile("s_waitcnt lgkmcnt(" #n ")" ::: "memory")
; #define PG8_BAR __builtin_amdgcn_s_barrier()
; #define PG8_SCHED __builtin_amdgcn_sched_barrier(0)
; template <class Epi, class Sched, bool ALIGN_EPI = false, bool SP2 = false>
; __device__ __forceinline__ void gemm_phase(PG8_LAS unsigned char* lds, const Gemm g, const Sched& S, const Epi& E, const int wave_s) {
;     ...
;             PG8_WAIT_V(8); PG8_WAIT_L(0); PG8_BAR; PG8_MMA(1, 0, At, B0); PG8_MMA(1, 1, At, B1); PG8_BAR; PG8_SCHED;
;             PG8_LDB(B0, 1, 0); PG8_LDB(B1, 1, 1); PG8_SCHED; PG8_LDA(At, 1, 0); PG8_STAGE(PG8_SA(0, 1), a2 + hstep, voffA);
;             PG8_WAIT_V(8); PG8_WAIT_L(0); PG8_BAR; PG8_MMA(0, 0, At, B0); PG8_MMA(0, 1, At, B1); PG8_BAR; PG8_SCHED;
	s_setprio 1
	s_waitcnt lgkmcnt(0)
	v_mfma_f32_16x16x32_bf16 v[62:65], v[130:133], v[164:167], v[62:65]
	v_mfma_f32_16x16x32_bf16 v[62:65], v[134:137], v[182:185], v[62:65]
	v_mfma_f32_16x16x32_bf16 v[58:61], v[138:141], v[164:167], v[58:61]
	v_mfma_f32_16x16x32_bf16 v[58:61], v[142:145], v[182:185], v[58:61]
	v_mfma_f32_16x16x32_bf16 v[46:49], v[130:133], v[186:189], v[46:49]
	v_mfma_f32_16x16x32_bf16 v[46:49], v[134:137], v[190:193], v[46:49]
	v_mfma_f32_16x16x32_bf16 v[42:45], v[138:141], v[186:189], v[42:45]
	v_mfma_f32_16x16x32_bf16 v[42:45], v[142:145], v[190:193], v[42:45]
	v_mfma_f32_16x16x32_bf16 v[30:33], v[130:133], v[194:197], v[30:33]
	v_mfma_f32_16x16x32_bf16 v[30:33], v[134:137], v[198:201], v[30:33]
	v_mfma_f32_16x16x32_bf16 v[26:29], v[138:141], v[194:197], v[26:29]
	v_mfma_f32_16x16x32_bf16 v[26:29], v[142:145], v[198:201], v[26:29]
	v_mfma_f32_16x16x32_bf16 v[14:17], v[130:133], v[212:215], v[14:17]
	v_mfma_f32_16x16x32_bf16 v[14:17], v[134:137], v[216:219], v[14:17]
	v_mfma_f32_16x16x32_bf16 v[10:13], v[138:141], v[212:215], v[10:13]
	v_mfma_f32_16x16x32_bf16 v[10:13], v[142:145], v[216:219], v[10:13]
	s_setprio 0
	s_setprio 1
	v_mfma_f32_16x16x32_bf16 v[54:57], v[146:149], v[164:167], v[54:57]
	v_mfma_f32_16x16x32_bf16 v[54:57], v[150:153], v[182:185], v[54:57]
	v_mfma_f32_16x16x32_bf16 v[50:53], v[154:157], v[164:167], v[50:53]
	v_mfma_f32_16x16x32_bf16 v[50:53], v[160:163], v[182:185], v[50:53]
	v_mfma_f32_16x16x32_bf16 v[38:41], v[146:149], v[186:189], v[38:41]
	v_mfma_f32_16x16x32_bf16 v[38:41], v[150:153], v[190:193], v[38:41]
	v_mfma_f32_16x16x32_bf16 v[34:37], v[154:157], v[186:189], v[34:37]
	v_mfma_f32_16x16x32_bf16 v[34:37], v[160:163], v[190:193], v[34:37]
	v_mfma_f32_16x16x32_bf16 v[22:25], v[146:149], v[194:197], v[22:25]
	v_mfma_f32_16x16x32_bf16 v[22:25], v[150:153], v[198:201], v[22:25]
	v_mfma_f32_16x16x32_bf16 v[18:21], v[154:157], v[194:197], v[18:21]
	v_mfma_f32_16x16x32_bf16 v[18:21], v[160:163], v[198:201], v[18:21]
	v_mfma_f32_16x16x32_bf16 v[6:9], v[146:149], v[212:215], v[6:9]
	v_mfma_f32_16x16x32_bf16 v[6:9], v[150:153], v[216:219], v[6:9]
	v_mfma_f32_16x16x32_bf16 v[2:5], v[154:157], v[212:215], v[2:5]
	v_mfma_f32_16x16x32_bf16 v[2:5], v[160:163], v[216:219], v[2:5]
	s_setprio 0
	s_barrier
	s_add_i32 s51, 0, 0x18000
	s_add_i32 s52, 0, 0x1c000
	v_add_u32_e32 v142, s51, v205
	v_add_u32_e32 v160, s52, v205
	ds_read_b128 v[130:133], v142
	ds_read_b128 v[134:137], v142 offset:1024
	ds_read_b128 v[138:141], v142 offset:2048
	ds_read_b128 v[142:145], v142 offset:3072
	ds_read_b128 v[146:149], v160
	ds_read_b128 v[150:153], v160 offset:1024
	ds_read_b128 v[154:157], v160 offset:2048
	ds_read_b128 v[160:163], v160 offset:3072
	s_add_u32 s48, s48, 0x100000
	s_addc_u32 s49, s49, 0
	s_mov_b32 m0, s7
	v_lshl_add_u64 v[228:229], s[48:49], 0, v[172:173]
	ds_read_b128 v[164:167], v208 offset:32768
	ds_read_b128 v[182:185], v208 offset:33792
	ds_read_b128 v[186:189], v208 offset:34816
	ds_read_b128 v[190:193], v208 offset:35840
	ds_read_b128 v[194:197], v208 offset:36864
	ds_read_b128 v[198:201], v208 offset:37888
	ds_read_b128 v[212:215], v208 offset:38912
	ds_read_b128 v[216:219], v208 offset:39936
	global_load_lds_dwordx4 v[228:229], off
	v_lshl_add_u64 v[228:229], s[48:49], 0, v[168:169]
	s_mov_b32 m0, s8
	s_nop 0
	global_load_lds_dwordx4 v[228:229], off
	s_waitcnt vmcnt(8)
	s_waitcnt lgkmcnt(0)
	s_barrier
	s_setprio 1
	s_waitcnt lgkmcnt(0)
	v_mfma_f32_16x16x32_bf16 v[126:129], v[130:133], v[164:167], v[126:129]
	v_mfma_f32_16x16x32_bf16 v[126:129], v[134:137], v[182:185], v[126:129]
	v_mfma_f32_16x16x32_bf16 v[122:125], v[138:141], v[164:167], v[122:125]
	v_mfma_f32_16x16x32_bf16 v[122:125], v[142:145], v[182:185], v[122:125]
	v_mfma_f32_16x16x32_bf16 v[110:113], v[130:133], v[186:189], v[110:113]
	v_mfma_f32_16x16x32_bf16 v[110:113], v[134:137], v[190:193], v[110:113]
	v_mfma_f32_16x16x32_bf16 v[106:109], v[138:141], v[186:189], v[106:109]
	v_mfma_f32_16x16x32_bf16 v[106:109], v[142:145], v[190:193], v[106:109]
	v_mfma_f32_16x16x32_bf16 v[94:97], v[130:133], v[194:197], v[94:97]
	v_mfma_f32_16x16x32_bf16 v[94:97], v[134:137], v[198:201], v[94:97]
	v_mfma_f32_16x16x32_bf16 v[90:93], v[138:141], v[194:197], v[90:93]
	v_mfma_f32_16x16x32_bf16 v[90:93], v[142:145], v[198:201], v[90:93]
	v_mfma_f32_16x16x32_bf16 v[78:81], v[130:133], v[212:215], v[78:81]
	v_mfma_f32_16x16x32_bf16 v[78:81], v[134:137], v[216:219], v[78:81]
	v_mfma_f32_16x16x32_bf16 v[74:77], v[138:141], v[212:215], v[74:77]
	v_mfma_f32_16x16x32_bf16 v[74:77], v[142:145], v[216:219], v[74:77]
	s_setprio 0
	s_setprio 1
	v_mfma_f32_16x16x32_bf16 v[118:121], v[146:149], v[164:167], v[118:121]
	v_mfma_f32_16x16x32_bf16 v[118:121], v[150:153], v[182:185], v[118:121]
	v_mfma_f32_16x16x32_bf16 v[114:117], v[154:157], v[164:167], v[114:117]
	v_mfma_f32_16x16x32_bf16 v[114:117], v[160:163], v[182:185], v[114:117]
	v_mfma_f32_16x16x32_bf16 v[102:105], v[146:149], v[186:189], v[102:105]
	v_mfma_f32_16x16x32_bf16 v[102:105], v[150:153], v[190:193], v[102:105]
	v_mfma_f32_16x16x32_bf16 v[98:101], v[154:157], v[186:189], v[98:101]
	v_mfma_f32_16x16x32_bf16 v[98:101], v[160:163], v[190:193], v[98:101]
	v_mfma_f32_16x16x32_bf16 v[86:89], v[146:149], v[194:197], v[86:89]
	v_mfma_f32_16x16x32_bf16 v[86:89], v[150:153], v[198:201], v[86:89]
	v_mfma_f32_16x16x32_bf16 v[82:85], v[154:157], v[194:197], v[82:85]
	v_mfma_f32_16x16x32_bf16 v[82:85], v[160:163], v[198:201], v[82:85]
	v_mfma_f32_16x16x32_bf16 v[70:73], v[146:149], v[212:215], v[70:73]
	v_mfma_f32_16x16x32_bf16 v[70:73], v[150:153], v[216:219], v[70:73]
	v_mfma_f32_16x16x32_bf16 v[66:69], v[154:157], v[212:215], v[66:69]
	v_mfma_f32_16x16x32_bf16 v[66:69], v[160:163], v[216:219], v[66:69]
	s_setprio 0
	s_barrier
; #define PG8_STAGE(bufoff, gbase, voff) do { _Pragma("unroll") for (int _i = 0; _i < 2; ++_i) \
;         __builtin_amdgcn_global_load_lds((const unsigned*)((const char*)(gbase) + (voff)[_i]), (PG8_LAS unsigned*)(lds + (bufoff) + ldsw + _i * 8192), 16, 0, 0); } while (0)
; #define PG8_LDA(dst, b, h) do { _Pragma("unroll") for (int m = 0; m < 4; ++m) _Pragma("unroll") for (int k = 0; k < 2; ++k) dst[m][k] = *(const PG8_LAS bf16x8*)(lds + PG8_SA(b, h) + aoff + m * 2048 + k * 1024); } while (0)
; #define PG8_MMA(ai, bj, At, Bt) do { __builtin_amdgcn_s_setprio(1); _Pragma("unroll") for (int m = 0; m < 4; ++m) _Pragma("unroll") for (int n = 0; n < 2; ++n) _Pragma("unroll") for (int k = 0; k < 2; ++k) \
;         acc[ai][bj][m][n] = __builtin_amdgcn_mfma_f32_16x16x32_bf16(Bt[n][k], At[m][k], acc[ai][bj][m][n], 0, 0, 0); __builtin_amdgcn_s_setprio(0); } while (0)
; #define PG8_WAIT_V(n) asm volatile("s_waitcnt vmcnt(" #n ")" ::: "memory")
; #define PG8_WAIT_L(n) asm volatile("s_waitcnt lgkmcnt(" #n ")" ::: "memory")
; #define PG8_BAR __builtin_amdgcn_s_barrier()
; #define PG8_SCHED __builtin_amdgcn_sched_barrier(0)
; template <class Epi, class Sched, bool ALIGN_EPI = false, bool SP2 = false>
; __device__ __forceinline__ void gemm_phase(PG8_LAS unsigned char* lds, const Gemm g, const Sched& S, const Epi& E, const int wave_s) {
;     ...
;             PG8_LDA(At, 1, 1); PG8_STAGE(PG8_SB(1, 0), b3, voffB); PG8_STAGE(PG8_SB(1, 1), b3 + bhstep, voffB); PG8_STAGE(PG8_SA(1, 0), a3, voffA);
;             PG8_WAIT_V(8); PG8_WAIT_L(0); PG8_BAR; PG8_MMA(1, 0, At, B0); PG8_MMA(1, 1, At, B1); PG8_BAR; PG8_SCHED;
	s_add_i32 s48, s51, s4
	v_lshl_add_u64 v[220:221], v[220:221], 0, s[24:25]
	s_mov_b32 m0, s48
	ds_read_b128 v[164:167], v208 offset:49152
	ds_read_b128 v[182:185], v208 offset:50176
	ds_read_b128 v[186:189], v208 offset:51200
	ds_read_b128 v[190:193], v208 offset:52224
	ds_read_b128 v[194:197], v208 offset:53248
	ds_read_b128 v[198:201], v208 offset:54272
	ds_read_b128 v[212:215], v208 offset:55296
	ds_read_b128 v[216:219], v208 offset:56320
	global_load_lds_dwordx4 v[220:221], off
	s_add_i32 m0, s48, 0x2000
	s_add_u32 s46, s46, 0x40080
	v_lshl_add_u64 v[220:221], v[222:223], 0, s[24:25]
	s_addc_u32 s47, s47, 0
	s_add_i32 s48, s52, s4
	global_load_lds_dwordx4 v[220:221], off
	v_lshl_add_u64 v[220:221], s[46:47], 0, v[170:171]
	s_mov_b32 m0, s48
	s_nop 0
	global_load_lds_dwordx4 v[220:221], off
	v_lshl_add_u64 v[220:221], s[46:47], 0, v[158:159]
	s_add_i32 m0, s48, 0x2000
	s_nop 0
	global_load_lds_dwordx4 v[220:221], off
	v_lshl_add_u64 v[220:221], v[224:225], 0, s[24:25]
	s_mov_b32 m0, s11
	s_nop 0
	global_load_lds_dwordx4 v[220:221], off
	v_lshl_add_u64 v[220:221], v[226:227], 0, s[24:25]
	s_mov_b32 m0, s12
	s_nop 0
	global_load_lds_dwordx4 v[220:221], off
	s_waitcnt vmcnt(8)
	s_waitcnt lgkmcnt(0)
	s_barrier
	s_setprio 1
	s_waitcnt lgkmcnt(0)
	v_mfma_f32_16x16x32_bf16 v[62:65], v[130:133], v[164:167], v[62:65]
	v_mfma_f32_16x16x32_bf16 v[62:65], v[134:137], v[182:185], v[62:65]
	v_mfma_f32_16x16x32_bf16 v[58:61], v[138:141], v[164:167], v[58:61]
	v_mfma_f32_16x16x32_bf16 v[58:61], v[142:145], v[182:185], v[58:61]
	v_mfma_f32_16x16x32_bf16 v[46:49], v[130:133], v[186:189], v[46:49]
	v_mfma_f32_16x16x32_bf16 v[46:49], v[134:137], v[190:193], v[46:49]
	v_mfma_f32_16x16x32_bf16 v[42:45], v[138:141], v[186:189], v[42:45]
	v_mfma_f32_16x16x32_bf16 v[42:45], v[142:145], v[190:193], v[42:45]
	v_mfma_f32_16x16x32_bf16 v[30:33], v[130:133], v[194:197], v[30:33]
	v_mfma_f32_16x16x32_bf16 v[30:33], v[134:137], v[198:201], v[30:33]
	v_mfma_f32_16x16x32_bf16 v[26:29], v[138:141], v[194:197], v[26:29]
	v_mfma_f32_16x16x32_bf16 v[26:29], v[142:145], v[198:201], v[26:29]
	v_mfma_f32_16x16x32_bf16 v[14:17], v[130:133], v[212:215], v[14:17]
	v_mfma_f32_16x16x32_bf16 v[14:17], v[134:137], v[216:219], v[14:17]
	v_mfma_f32_16x16x32_bf16 v[10:13], v[138:141], v[212:215], v[10:13]
	v_mfma_f32_16x16x32_bf16 v[10:13], v[142:145], v[216:219], v[10:13]
	s_setprio 0
	s_setprio 1
	v_mfma_f32_16x16x32_bf16 v[54:57], v[146:149], v[164:167], v[54:57]
	v_mfma_f32_16x16x32_bf16 v[54:57], v[150:153], v[182:185], v[54:57]
	v_mfma_f32_16x16x32_bf16 v[50:53], v[154:157], v[164:167], v[50:53]
	v_mfma_f32_16x16x32_bf16 v[50:53], v[160:163], v[182:185], v[50:53]
	v_mfma_f32_16x16x32_bf16 v[38:41], v[146:149], v[186:189], v[38:41]
	v_mfma_f32_16x16x32_bf16 v[38:41], v[150:153], v[190:193], v[38:41]
	v_mfma_f32_16x16x32_bf16 v[34:37], v[154:157], v[186:189], v[34:37]
	v_mfma_f32_16x16x32_bf16 v[34:37], v[160:163], v[190:193], v[34:37]
	v_mfma_f32_16x16x32_bf16 v[22:25], v[146:149], v[194:197], v[22:25]
	v_mfma_f32_16x16x32_bf16 v[22:25], v[150:153], v[198:201], v[22:25]
	v_mfma_f32_16x16x32_bf16 v[18:21], v[154:157], v[194:197], v[18:21]
	v_mfma_f32_16x16x32_bf16 v[18:21], v[160:163], v[198:201], v[18:21]
	v_mfma_f32_16x16x32_bf16 v[6:9], v[146:149], v[212:215], v[6:9]
	v_mfma_f32_16x16x32_bf16 v[6:9], v[150:153], v[216:219], v[6:9]
	v_mfma_f32_16x16x32_bf16 v[2:5], v[154:157], v[212:215], v[2:5]
	v_mfma_f32_16x16x32_bf16 v[2:5], v[160:163], v[216:219], v[2:5]
	s_setprio 0
	s_barrier
	s_add_i32 s50, s50, 2
	s_add_u32 s42, s42, 0x100
	s_addc_u32 s43, s43, 0
	s_add_u32 s29, s29, 0x100
	s_addc_u32 s45, s45, 0
	s_cmp_gt_u32 s50, 61
	s_cbranch_scc0 .LBB0_923
	s_and_b64 vcc, exec, s[20:21]
	s_cbranch_vccz .LBB0_926
	s_barrier
